# GEMM main loops: 4 of the 6 LDS-DMA pieces of each 6-piece load segment issued inside the following MFMA block (segment wait vmcnt(8)->vmcnt(4))
# baseline (speedup 1.0000x reference)
.LBB0_159:
	ds_read_b128 v[150:153], v147
	ds_read_b128 v[154:157], v147 offset:1024
	ds_read_b128 v[158:161], v147 offset:2048
	ds_read_b128 v[162:165], v147 offset:3072
	ds_read_b128 v[166:169], v148
	ds_read_b128 v[170:173], v148 offset:1024
	ds_read_b128 v[174:177], v148 offset:2048
	ds_read_b128 v[178:181], v148 offset:3072
	s_add_u32 s38, s36, 0x100
	s_addc_u32 s39, s37, 0
	s_cmp_eq_u32 s59, 28
	s_cselect_b32 s43, s19, s39
	s_cselect_b32 s42, s55, s38
	s_cselect_b32 s41, s17, s58
	s_cselect_b32 s40, s56, s57
	v_lshl_add_u64 v[182:183], s[36:37], 0, v[136:137]
	s_add_i32 m0, s35, 0xc000
	s_nop 0
	global_load_lds_dwordx4 v[182:183], off
	v_lshl_add_u64 v[182:183], s[36:37], 0, v[138:139]
	s_add_i32 m0, s35, 0xe000
	s_nop 0
	global_load_lds_dwordx4 v[182:183], off
	ds_read_b128 v[182:185], v149
	ds_read_b128 v[186:189], v149 offset:1024
	ds_read_b128 v[190:193], v149 offset:2048
	ds_read_b128 v[194:197], v149 offset:3072
	ds_read_b128 v[198:201], v149 offset:4096
	ds_read_b128 v[202:205], v149 offset:5120
	ds_read_b128 v[206:209], v149 offset:6144
	ds_read_b128 v[210:213], v149 offset:7168
	s_waitcnt vmcnt(8)
	s_waitcnt lgkmcnt(0)
	s_barrier
	s_setprio 1
	s_waitcnt lgkmcnt(0)
	v_mfma_f32_16x16x32_bf16 v[124:127], v[150:153], v[182:185], v[124:127]
	v_mfma_f32_16x16x32_bf16 v[120:123], v[158:161], v[182:185], v[120:123]
	v_mfma_f32_16x16x32_bf16 v[108:111], v[150:153], v[190:193], v[108:111]
	v_mfma_f32_16x16x32_bf16 v[104:107], v[158:161], v[190:193], v[104:107]
	v_mfma_f32_16x16x32_bf16 v[92:95], v[150:153], v[198:201], v[92:95]
	v_mfma_f32_16x16x32_bf16 v[88:91], v[158:161], v[198:201], v[88:91]
	v_mfma_f32_16x16x32_bf16 v[76:79], v[150:153], v[206:209], v[76:79]
	v_mfma_f32_16x16x32_bf16 v[72:75], v[158:161], v[206:209], v[72:75]
	v_mfma_f32_16x16x32_bf16 v[124:127], v[154:157], v[186:189], v[124:127]
	v_mfma_f32_16x16x32_bf16 v[120:123], v[162:165], v[186:189], v[120:123]
	v_mfma_f32_16x16x32_bf16 v[108:111], v[154:157], v[194:197], v[108:111]
	v_mfma_f32_16x16x32_bf16 v[104:107], v[162:165], v[194:197], v[104:107]
	v_mfma_f32_16x16x32_bf16 v[92:95], v[154:157], v[202:205], v[92:95]
	v_mfma_f32_16x16x32_bf16 v[88:91], v[162:165], v[202:205], v[88:91]
	v_mfma_f32_16x16x32_bf16 v[76:79], v[154:157], v[210:213], v[76:79]
	v_mfma_f32_16x16x32_bf16 v[72:75], v[162:165], v[210:213], v[72:75]
	s_setprio 0
	s_setprio 1
	v_mfma_f32_16x16x32_bf16 v[116:119], v[166:169], v[182:185], v[116:119]
	v_mfma_f32_16x16x32_bf16 v[112:115], v[174:177], v[182:185], v[112:115]
	v_mfma_f32_16x16x32_bf16 v[100:103], v[166:169], v[190:193], v[100:103]
	v_mfma_f32_16x16x32_bf16 v[96:99], v[174:177], v[190:193], v[96:99]
	v_mfma_f32_16x16x32_bf16 v[84:87], v[166:169], v[198:201], v[84:87]
	v_mfma_f32_16x16x32_bf16 v[80:83], v[174:177], v[198:201], v[80:83]
	v_mfma_f32_16x16x32_bf16 v[68:71], v[166:169], v[206:209], v[68:71]
	v_mfma_f32_16x16x32_bf16 v[64:67], v[174:177], v[206:209], v[64:67]
	v_mfma_f32_16x16x32_bf16 v[116:119], v[170:173], v[186:189], v[116:119]
	v_mfma_f32_16x16x32_bf16 v[112:115], v[178:181], v[186:189], v[112:115]
	v_mfma_f32_16x16x32_bf16 v[100:103], v[170:173], v[194:197], v[100:103]
	v_mfma_f32_16x16x32_bf16 v[96:99], v[178:181], v[194:197], v[96:99]
	v_mfma_f32_16x16x32_bf16 v[84:87], v[170:173], v[202:205], v[84:87]
	v_mfma_f32_16x16x32_bf16 v[80:83], v[178:181], v[202:205], v[80:83]
	v_mfma_f32_16x16x32_bf16 v[68:71], v[170:173], v[210:213], v[68:71]
	v_mfma_f32_16x16x32_bf16 v[64:67], v[178:181], v[210:213], v[64:67]
	s_setprio 0
	s_barrier
	s_add_i32 s36, s51, s11
	v_lshl_add_u64 v[214:215], s[40:41], 0, v[130:131]
	s_mov_b32 m0, s36
	v_lshl_add_u64 v[216:217], s[40:41], 0, v[134:135]
	global_load_lds_dwordx4 v[214:215], off
	s_add_i32 m0, s36, 0x2000
	s_add_u32 s36, s40, 0x80000
	s_addc_u32 s37, s41, 0
	s_add_i32 s60, s52, s11
	global_load_lds_dwordx4 v[216:217], off
	v_lshl_add_u64 v[218:219], s[42:43], 0, v[128:129]
	v_lshl_add_u64 v[220:221], s[42:43], 0, v[132:133]
	ds_read_b128 v[182:185], v149 offset:16384
	ds_read_b128 v[186:189], v149 offset:17408
	ds_read_b128 v[190:193], v149 offset:18432
	ds_read_b128 v[194:197], v149 offset:19456
	ds_read_b128 v[198:201], v149 offset:20480
	ds_read_b128 v[202:205], v149 offset:21504
	ds_read_b128 v[206:209], v149 offset:22528
	ds_read_b128 v[210:213], v149 offset:23552
	s_waitcnt vmcnt(4)
	s_waitcnt lgkmcnt(0)
	s_barrier
	s_setprio 1
	s_waitcnt lgkmcnt(0)
	v_mfma_f32_16x16x32_bf16 v[60:63], v[150:153], v[182:185], v[60:63]
	v_mfma_f32_16x16x32_bf16 v[56:59], v[158:161], v[182:185], v[56:59]
	v_lshl_add_u64 v[228:229], s[36:37], 0, v[130:131]
	s_mov_b32 m0, s60
	s_nop 0
	global_load_lds_dwordx4 v[228:229], off
	v_mfma_f32_16x16x32_bf16 v[44:47], v[150:153], v[190:193], v[44:47]
	v_mfma_f32_16x16x32_bf16 v[40:43], v[158:161], v[190:193], v[40:43]
	v_mfma_f32_16x16x32_bf16 v[28:31], v[150:153], v[198:201], v[28:31]
	v_mfma_f32_16x16x32_bf16 v[24:27], v[158:161], v[198:201], v[24:27]
	v_lshl_add_u64 v[228:229], s[36:37], 0, v[134:135]
	s_add_i32 m0, s60, 0x2000
	s_nop 0
	global_load_lds_dwordx4 v[228:229], off
	v_mfma_f32_16x16x32_bf16 v[12:15], v[150:153], v[206:209], v[12:15]
	v_mfma_f32_16x16x32_bf16 v[8:11], v[158:161], v[206:209], v[8:11]
	v_mfma_f32_16x16x32_bf16 v[60:63], v[154:157], v[186:189], v[60:63]
	v_mfma_f32_16x16x32_bf16 v[56:59], v[162:165], v[186:189], v[56:59]
	s_mov_b32 m0, s35
	s_nop 0
	global_load_lds_dwordx4 v[218:219], off
	v_mfma_f32_16x16x32_bf16 v[44:47], v[154:157], v[194:197], v[44:47]
	v_mfma_f32_16x16x32_bf16 v[40:43], v[162:165], v[194:197], v[40:43]
	v_mfma_f32_16x16x32_bf16 v[28:31], v[154:157], v[202:205], v[28:31]
	v_mfma_f32_16x16x32_bf16 v[24:27], v[162:165], v[202:205], v[24:27]
	s_mov_b32 m0, s44
	s_nop 0
	global_load_lds_dwordx4 v[220:221], off
	v_mfma_f32_16x16x32_bf16 v[12:15], v[154:157], v[210:213], v[12:15]
	v_mfma_f32_16x16x32_bf16 v[8:11], v[162:165], v[210:213], v[8:11]
	s_setprio 0
	s_setprio 1
	v_mfma_f32_16x16x32_bf16 v[52:55], v[166:169], v[182:185], v[52:55]
	v_mfma_f32_16x16x32_bf16 v[48:51], v[174:177], v[182:185], v[48:51]
	v_mfma_f32_16x16x32_bf16 v[36:39], v[166:169], v[190:193], v[36:39]
	v_mfma_f32_16x16x32_bf16 v[32:35], v[174:177], v[190:193], v[32:35]
	v_mfma_f32_16x16x32_bf16 v[20:23], v[166:169], v[198:201], v[20:23]
	v_mfma_f32_16x16x32_bf16 v[16:19], v[174:177], v[198:201], v[16:19]
	v_mfma_f32_16x16x32_bf16 v[4:7], v[166:169], v[206:209], v[4:7]
	v_mfma_f32_16x16x32_bf16 v[0:3], v[174:177], v[206:209], v[0:3]
	v_mfma_f32_16x16x32_bf16 v[52:55], v[170:173], v[186:189], v[52:55]
	v_mfma_f32_16x16x32_bf16 v[48:51], v[178:181], v[186:189], v[48:51]
	v_mfma_f32_16x16x32_bf16 v[36:39], v[170:173], v[194:197], v[36:39]
	v_mfma_f32_16x16x32_bf16 v[32:35], v[178:181], v[194:197], v[32:35]
	v_mfma_f32_16x16x32_bf16 v[20:23], v[170:173], v[202:205], v[20:23]
	v_mfma_f32_16x16x32_bf16 v[16:19], v[178:181], v[202:205], v[16:19]
	v_mfma_f32_16x16x32_bf16 v[4:7], v[170:173], v[210:213], v[4:7]
	v_mfma_f32_16x16x32_bf16 v[0:3], v[178:181], v[210:213], v[0:3]
	s_setprio 0
	s_barrier
	s_add_i32 s60, 0, 0x18000
	s_add_i32 s61, 0, 0x1c000
	v_add_u32_e32 v162, s60, v144
	v_add_u32_e32 v178, s61, v144
	ds_read_b128 v[150:153], v162
	ds_read_b128 v[154:157], v162 offset:1024
	ds_read_b128 v[158:161], v162 offset:2048
	ds_read_b128 v[162:165], v162 offset:3072
	ds_read_b128 v[166:169], v178
	ds_read_b128 v[170:173], v178 offset:1024
	ds_read_b128 v[174:177], v178 offset:2048
	ds_read_b128 v[178:181], v178 offset:3072
	s_add_u32 s36, s42, 0x80000
	s_addc_u32 s37, s43, 0
	s_mov_b32 m0, s45
	v_lshl_add_u64 v[182:183], s[36:37], 0, v[128:129]
	global_load_lds_dwordx4 v[182:183], off
	v_lshl_add_u64 v[182:183], s[36:37], 0, v[132:133]
	s_mov_b32 m0, s46
	s_nop 0
	global_load_lds_dwordx4 v[182:183], off
	ds_read_b128 v[182:185], v149 offset:32768
	ds_read_b128 v[186:189], v149 offset:33792
	ds_read_b128 v[190:193], v149 offset:34816
	ds_read_b128 v[194:197], v149 offset:35840
	ds_read_b128 v[198:201], v149 offset:36864
	ds_read_b128 v[202:205], v149 offset:37888
	ds_read_b128 v[206:209], v149 offset:38912
	ds_read_b128 v[210:213], v149 offset:39936
	s_waitcnt vmcnt(8)
	s_waitcnt lgkmcnt(0)
	s_barrier
	s_setprio 1
	s_waitcnt lgkmcnt(0)
	v_mfma_f32_16x16x32_bf16 v[124:127], v[150:153], v[182:185], v[124:127]
	v_mfma_f32_16x16x32_bf16 v[120:123], v[158:161], v[182:185], v[120:123]
	v_mfma_f32_16x16x32_bf16 v[108:111], v[150:153], v[190:193], v[108:111]
	v_mfma_f32_16x16x32_bf16 v[104:107], v[158:161], v[190:193], v[104:107]
	v_mfma_f32_16x16x32_bf16 v[92:95], v[150:153], v[198:201], v[92:95]
	v_mfma_f32_16x16x32_bf16 v[88:91], v[158:161], v[198:201], v[88:91]
	v_mfma_f32_16x16x32_bf16 v[76:79], v[150:153], v[206:209], v[76:79]
	v_mfma_f32_16x16x32_bf16 v[72:75], v[158:161], v[206:209], v[72:75]
	v_mfma_f32_16x16x32_bf16 v[124:127], v[154:157], v[186:189], v[124:127]
	v_mfma_f32_16x16x32_bf16 v[120:123], v[162:165], v[186:189], v[120:123]
	v_mfma_f32_16x16x32_bf16 v[108:111], v[154:157], v[194:197], v[108:111]
	v_mfma_f32_16x16x32_bf16 v[104:107], v[162:165], v[194:197], v[104:107]
	v_mfma_f32_16x16x32_bf16 v[92:95], v[154:157], v[202:205], v[92:95]
	v_mfma_f32_16x16x32_bf16 v[88:91], v[162:165], v[202:205], v[88:91]
	v_mfma_f32_16x16x32_bf16 v[76:79], v[154:157], v[210:213], v[76:79]
	v_mfma_f32_16x16x32_bf16 v[72:75], v[162:165], v[210:213], v[72:75]
	s_setprio 0
	s_setprio 1
	v_mfma_f32_16x16x32_bf16 v[116:119], v[166:169], v[182:185], v[116:119]
	v_mfma_f32_16x16x32_bf16 v[112:115], v[174:177], v[182:185], v[112:115]
	v_mfma_f32_16x16x32_bf16 v[100:103], v[166:169], v[190:193], v[100:103]
	v_mfma_f32_16x16x32_bf16 v[96:99], v[174:177], v[190:193], v[96:99]
	v_mfma_f32_16x16x32_bf16 v[84:87], v[166:169], v[198:201], v[84:87]
	v_mfma_f32_16x16x32_bf16 v[80:83], v[174:177], v[198:201], v[80:83]
	v_mfma_f32_16x16x32_bf16 v[68:71], v[166:169], v[206:209], v[68:71]
	v_mfma_f32_16x16x32_bf16 v[64:67], v[174:177], v[206:209], v[64:67]
	v_mfma_f32_16x16x32_bf16 v[116:119], v[170:173], v[186:189], v[116:119]
	v_mfma_f32_16x16x32_bf16 v[112:115], v[178:181], v[186:189], v[112:115]
	v_mfma_f32_16x16x32_bf16 v[100:103], v[170:173], v[194:197], v[100:103]
	v_mfma_f32_16x16x32_bf16 v[96:99], v[178:181], v[194:197], v[96:99]
	v_mfma_f32_16x16x32_bf16 v[84:87], v[170:173], v[202:205], v[84:87]
	v_mfma_f32_16x16x32_bf16 v[80:83], v[178:181], v[202:205], v[80:83]
	v_mfma_f32_16x16x32_bf16 v[68:71], v[170:173], v[210:213], v[68:71]
	v_mfma_f32_16x16x32_bf16 v[64:67], v[178:181], v[210:213], v[64:67]
	s_setprio 0
	s_barrier
	s_add_i32 s36, s60, s11
	v_lshl_add_u64 v[182:183], v[214:215], 0, s[14:15]
	s_mov_b32 m0, s36
	s_nop 0
	global_load_lds_dwordx4 v[182:183], off
	s_add_i32 m0, s36, 0x2000
	s_add_u32 s36, s40, 0x80080
	v_lshl_add_u64 v[182:183], v[216:217], 0, s[14:15]
	s_addc_u32 s37, s41, 0
	s_add_i32 s40, s61, s11
	global_load_lds_dwordx4 v[182:183], off
	ds_read_b128 v[182:185], v149 offset:49152
	ds_read_b128 v[186:189], v149 offset:50176
	ds_read_b128 v[190:193], v149 offset:51200
	ds_read_b128 v[194:197], v149 offset:52224
	ds_read_b128 v[198:201], v149 offset:53248
	ds_read_b128 v[202:205], v149 offset:54272
	ds_read_b128 v[206:209], v149 offset:55296
	ds_read_b128 v[210:213], v149 offset:56320
	s_waitcnt vmcnt(4)
	s_waitcnt lgkmcnt(0)
	s_barrier
	s_setprio 1
	s_waitcnt lgkmcnt(0)
	v_mfma_f32_16x16x32_bf16 v[60:63], v[150:153], v[182:185], v[60:63]
	v_mfma_f32_16x16x32_bf16 v[56:59], v[158:161], v[182:185], v[56:59]
	v_lshl_add_u64 v[228:229], s[36:37], 0, v[130:131]
	s_mov_b32 m0, s40
	s_nop 0
	global_load_lds_dwordx4 v[228:229], off
	v_mfma_f32_16x16x32_bf16 v[44:47], v[150:153], v[190:193], v[44:47]
	v_mfma_f32_16x16x32_bf16 v[40:43], v[158:161], v[190:193], v[40:43]
	v_mfma_f32_16x16x32_bf16 v[28:31], v[150:153], v[198:201], v[28:31]
	v_mfma_f32_16x16x32_bf16 v[24:27], v[158:161], v[198:201], v[24:27]
	v_lshl_add_u64 v[228:229], s[36:37], 0, v[134:135]
	s_add_i32 m0, s40, 0x2000
	s_nop 0
	global_load_lds_dwordx4 v[228:229], off
	v_mfma_f32_16x16x32_bf16 v[12:15], v[150:153], v[206:209], v[12:15]
	v_mfma_f32_16x16x32_bf16 v[8:11], v[158:161], v[206:209], v[8:11]
	v_mfma_f32_16x16x32_bf16 v[60:63], v[154:157], v[186:189], v[60:63]
	v_mfma_f32_16x16x32_bf16 v[56:59], v[162:165], v[186:189], v[56:59]
	v_lshl_add_u64 v[228:229], v[218:219], 0, s[14:15]
	s_mov_b32 m0, s49
	s_nop 0
	global_load_lds_dwordx4 v[228:229], off
	v_mfma_f32_16x16x32_bf16 v[44:47], v[154:157], v[194:197], v[44:47]
	v_mfma_f32_16x16x32_bf16 v[40:43], v[162:165], v[194:197], v[40:43]
	v_mfma_f32_16x16x32_bf16 v[28:31], v[154:157], v[202:205], v[28:31]
	v_mfma_f32_16x16x32_bf16 v[24:27], v[162:165], v[202:205], v[24:27]
	v_lshl_add_u64 v[228:229], v[220:221], 0, s[14:15]
	s_mov_b32 m0, s50
	s_nop 0
	global_load_lds_dwordx4 v[228:229], off
	v_mfma_f32_16x16x32_bf16 v[12:15], v[154:157], v[210:213], v[12:15]
	v_mfma_f32_16x16x32_bf16 v[8:11], v[162:165], v[210:213], v[8:11]
	s_setprio 0
	s_setprio 1
	v_mfma_f32_16x16x32_bf16 v[52:55], v[166:169], v[182:185], v[52:55]
	v_mfma_f32_16x16x32_bf16 v[48:51], v[174:177], v[182:185], v[48:51]
	v_mfma_f32_16x16x32_bf16 v[36:39], v[166:169], v[190:193], v[36:39]
	v_mfma_f32_16x16x32_bf16 v[32:35], v[174:177], v[190:193], v[32:35]
	v_mfma_f32_16x16x32_bf16 v[20:23], v[166:169], v[198:201], v[20:23]
	v_mfma_f32_16x16x32_bf16 v[16:19], v[174:177], v[198:201], v[16:19]
	v_mfma_f32_16x16x32_bf16 v[4:7], v[166:169], v[206:209], v[4:7]
	v_mfma_f32_16x16x32_bf16 v[0:3], v[174:177], v[206:209], v[0:3]
	v_mfma_f32_16x16x32_bf16 v[52:55], v[170:173], v[186:189], v[52:55]
	v_mfma_f32_16x16x32_bf16 v[48:51], v[178:181], v[186:189], v[48:51]
	v_mfma_f32_16x16x32_bf16 v[36:39], v[170:173], v[194:197], v[36:39]
	v_mfma_f32_16x16x32_bf16 v[32:35], v[178:181], v[194:197], v[32:35]
	v_mfma_f32_16x16x32_bf16 v[20:23], v[170:173], v[202:205], v[20:23]
	v_mfma_f32_16x16x32_bf16 v[16:19], v[178:181], v[202:205], v[16:19]
	v_mfma_f32_16x16x32_bf16 v[4:7], v[170:173], v[210:213], v[4:7]
	v_mfma_f32_16x16x32_bf16 v[0:3], v[178:181], v[210:213], v[0:3]
	s_setprio 0
	s_barrier
	s_add_i32 s59, s59, 2
	s_add_u32 s57, s57, 0x100
	s_addc_u32 s58, s58, 0
	s_cmp_gt_u32 s59, 29
	s_mov_b64 s[36:37], s[38:39]
	s_cbranch_scc0 .LBB0_159
	s_and_b64 vcc, exec, s[6:7]
	s_cbranch_vccz .LBB0_162
	s_barrier

.LBB0_248:
	ds_read_b128 v[144:147], v161
	ds_read_b128 v[148:151], v161 offset:1024
	ds_read_b128 v[152:155], v161 offset:2048
	ds_read_b128 v[164:167], v161 offset:3072
	ds_read_b128 v[168:171], v162
	ds_read_b128 v[172:175], v162 offset:1024
	ds_read_b128 v[176:179], v162 offset:2048
	ds_read_b128 v[180:183], v162 offset:3072
	s_add_u32 s6, s8, 0x100
	s_addc_u32 s7, s9, 0
	s_cmpk_eq_i32 s65, 0x54
	s_cselect_b32 s49, s43, s7
	s_cselect_b32 s48, s42, s6
	s_cselect_b32 s47, s45, s64
	s_cselect_b32 s46, s44, s63
	v_lshl_add_u64 v[184:185], s[8:9], 0, v[136:137]
	s_add_i32 m0, s53, 0xc000
	s_nop 0
	global_load_lds_dwordx4 v[184:185], off
	v_lshl_add_u64 v[184:185], s[8:9], 0, v[138:139]
	s_add_i32 m0, s53, 0xe000
	s_nop 0
	global_load_lds_dwordx4 v[184:185], off
	ds_read_b128 v[184:187], v163
	ds_read_b128 v[188:191], v163 offset:1024
	ds_read_b128 v[192:195], v163 offset:2048
	ds_read_b128 v[196:199], v163 offset:3072
	ds_read_b128 v[200:203], v163 offset:4096
	ds_read_b128 v[204:207], v163 offset:5120
	ds_read_b128 v[208:211], v163 offset:6144
	ds_read_b128 v[212:215], v163 offset:7168
	s_waitcnt vmcnt(8)
	s_waitcnt lgkmcnt(0)
	s_barrier
	s_setprio 1
	s_waitcnt lgkmcnt(0)
	v_mfma_f32_16x16x32_bf16 v[124:127], v[144:147], v[184:187], v[124:127]
	v_mfma_f32_16x16x32_bf16 v[120:123], v[152:155], v[184:187], v[120:123]
	v_mfma_f32_16x16x32_bf16 v[108:111], v[144:147], v[192:195], v[108:111]
	v_mfma_f32_16x16x32_bf16 v[104:107], v[152:155], v[192:195], v[104:107]
	v_mfma_f32_16x16x32_bf16 v[92:95], v[144:147], v[200:203], v[92:95]
	v_mfma_f32_16x16x32_bf16 v[88:91], v[152:155], v[200:203], v[88:91]
	v_mfma_f32_16x16x32_bf16 v[76:79], v[144:147], v[208:211], v[76:79]
	v_mfma_f32_16x16x32_bf16 v[72:75], v[152:155], v[208:211], v[72:75]
	v_mfma_f32_16x16x32_bf16 v[124:127], v[148:151], v[188:191], v[124:127]
	v_mfma_f32_16x16x32_bf16 v[120:123], v[164:167], v[188:191], v[120:123]
	v_mfma_f32_16x16x32_bf16 v[108:111], v[148:151], v[196:199], v[108:111]
	v_mfma_f32_16x16x32_bf16 v[104:107], v[164:167], v[196:199], v[104:107]
	v_mfma_f32_16x16x32_bf16 v[92:95], v[148:151], v[204:207], v[92:95]
	v_mfma_f32_16x16x32_bf16 v[88:91], v[164:167], v[204:207], v[88:91]
	v_mfma_f32_16x16x32_bf16 v[76:79], v[148:151], v[212:215], v[76:79]
	v_mfma_f32_16x16x32_bf16 v[72:75], v[164:167], v[212:215], v[72:75]
	s_setprio 0
	s_setprio 1
	v_mfma_f32_16x16x32_bf16 v[116:119], v[168:171], v[184:187], v[116:119]
	v_mfma_f32_16x16x32_bf16 v[112:115], v[176:179], v[184:187], v[112:115]
	v_mfma_f32_16x16x32_bf16 v[100:103], v[168:171], v[192:195], v[100:103]
	v_mfma_f32_16x16x32_bf16 v[96:99], v[176:179], v[192:195], v[96:99]
	v_mfma_f32_16x16x32_bf16 v[84:87], v[168:171], v[200:203], v[84:87]
	v_mfma_f32_16x16x32_bf16 v[80:83], v[176:179], v[200:203], v[80:83]
	v_mfma_f32_16x16x32_bf16 v[68:71], v[168:171], v[208:211], v[68:71]
	v_mfma_f32_16x16x32_bf16 v[64:67], v[176:179], v[208:211], v[64:67]
	v_mfma_f32_16x16x32_bf16 v[116:119], v[172:175], v[188:191], v[116:119]
	v_mfma_f32_16x16x32_bf16 v[112:115], v[180:183], v[188:191], v[112:115]
	v_mfma_f32_16x16x32_bf16 v[100:103], v[172:175], v[196:199], v[100:103]
	v_mfma_f32_16x16x32_bf16 v[96:99], v[180:183], v[196:199], v[96:99]
	v_mfma_f32_16x16x32_bf16 v[84:87], v[172:175], v[204:207], v[84:87]
	v_mfma_f32_16x16x32_bf16 v[80:83], v[180:183], v[204:207], v[80:83]
	v_mfma_f32_16x16x32_bf16 v[68:71], v[172:175], v[212:215], v[68:71]
	v_mfma_f32_16x16x32_bf16 v[64:67], v[180:183], v[212:215], v[64:67]
	s_setprio 0
	s_barrier
	s_add_i32 s8, s58, s21
	v_lshl_add_u64 v[216:217], s[46:47], 0, v[130:131]
	s_mov_b32 m0, s8
	v_lshl_add_u64 v[218:219], s[46:47], 0, v[134:135]
	global_load_lds_dwordx4 v[216:217], off
	s_add_i32 m0, s8, 0x2000
	s_add_u32 s8, s46, 0x160000
	s_addc_u32 s9, s47, 0
	s_add_i32 s66, s59, s21
	global_load_lds_dwordx4 v[218:219], off
	v_lshl_add_u64 v[220:221], s[48:49], 0, v[128:129]
	v_lshl_add_u64 v[222:223], s[48:49], 0, v[132:133]
	ds_read_b128 v[184:187], v163 offset:16384
	ds_read_b128 v[188:191], v163 offset:17408
	ds_read_b128 v[192:195], v163 offset:18432
	ds_read_b128 v[196:199], v163 offset:19456
	ds_read_b128 v[200:203], v163 offset:20480
	ds_read_b128 v[204:207], v163 offset:21504
	ds_read_b128 v[208:211], v163 offset:22528
	ds_read_b128 v[212:215], v163 offset:23552
	s_waitcnt vmcnt(4)
	s_waitcnt lgkmcnt(0)
	s_barrier
	s_setprio 1
	s_waitcnt lgkmcnt(0)
	v_mfma_f32_16x16x32_bf16 v[60:63], v[144:147], v[184:187], v[60:63]
	v_mfma_f32_16x16x32_bf16 v[56:59], v[152:155], v[184:187], v[56:59]
	v_lshl_add_u64 v[228:229], s[8:9], 0, v[130:131]
	s_mov_b32 m0, s66
	s_nop 0
	global_load_lds_dwordx4 v[228:229], off
	v_mfma_f32_16x16x32_bf16 v[44:47], v[144:147], v[192:195], v[44:47]
	v_mfma_f32_16x16x32_bf16 v[40:43], v[152:155], v[192:195], v[40:43]
	v_mfma_f32_16x16x32_bf16 v[28:31], v[144:147], v[200:203], v[28:31]
	v_mfma_f32_16x16x32_bf16 v[24:27], v[152:155], v[200:203], v[24:27]
	v_lshl_add_u64 v[228:229], s[8:9], 0, v[134:135]
	s_add_i32 m0, s66, 0x2000
	s_nop 0
	global_load_lds_dwordx4 v[228:229], off
	v_mfma_f32_16x16x32_bf16 v[12:15], v[144:147], v[208:211], v[12:15]
	v_mfma_f32_16x16x32_bf16 v[8:11], v[152:155], v[208:211], v[8:11]
	v_mfma_f32_16x16x32_bf16 v[60:63], v[148:151], v[188:191], v[60:63]
	v_mfma_f32_16x16x32_bf16 v[56:59], v[164:167], v[188:191], v[56:59]
	s_mov_b32 m0, s53
	s_nop 0
	global_load_lds_dwordx4 v[220:221], off
	v_mfma_f32_16x16x32_bf16 v[44:47], v[148:151], v[196:199], v[44:47]
	v_mfma_f32_16x16x32_bf16 v[40:43], v[164:167], v[196:199], v[40:43]
	v_mfma_f32_16x16x32_bf16 v[28:31], v[148:151], v[204:207], v[28:31]
	v_mfma_f32_16x16x32_bf16 v[24:27], v[164:167], v[204:207], v[24:27]
	s_mov_b32 m0, s54
	s_nop 0
	global_load_lds_dwordx4 v[222:223], off
	v_mfma_f32_16x16x32_bf16 v[12:15], v[148:151], v[212:215], v[12:15]
	v_mfma_f32_16x16x32_bf16 v[8:11], v[164:167], v[212:215], v[8:11]
	s_setprio 0
	s_setprio 1
	v_mfma_f32_16x16x32_bf16 v[52:55], v[168:171], v[184:187], v[52:55]
	v_mfma_f32_16x16x32_bf16 v[48:51], v[176:179], v[184:187], v[48:51]
	v_mfma_f32_16x16x32_bf16 v[36:39], v[168:171], v[192:195], v[36:39]
	v_mfma_f32_16x16x32_bf16 v[32:35], v[176:179], v[192:195], v[32:35]
	v_mfma_f32_16x16x32_bf16 v[20:23], v[168:171], v[200:203], v[20:23]
	v_mfma_f32_16x16x32_bf16 v[16:19], v[176:179], v[200:203], v[16:19]
	v_mfma_f32_16x16x32_bf16 v[4:7], v[168:171], v[208:211], v[4:7]
	v_mfma_f32_16x16x32_bf16 v[0:3], v[176:179], v[208:211], v[0:3]
	v_mfma_f32_16x16x32_bf16 v[52:55], v[172:175], v[188:191], v[52:55]
	v_mfma_f32_16x16x32_bf16 v[48:51], v[180:183], v[188:191], v[48:51]
	v_mfma_f32_16x16x32_bf16 v[36:39], v[172:175], v[196:199], v[36:39]
	v_mfma_f32_16x16x32_bf16 v[32:35], v[180:183], v[196:199], v[32:35]
	v_mfma_f32_16x16x32_bf16 v[20:23], v[172:175], v[204:207], v[20:23]
	v_mfma_f32_16x16x32_bf16 v[16:19], v[180:183], v[204:207], v[16:19]
	v_mfma_f32_16x16x32_bf16 v[4:7], v[172:175], v[212:215], v[4:7]
	v_mfma_f32_16x16x32_bf16 v[0:3], v[180:183], v[212:215], v[0:3]
	s_setprio 0
	s_barrier
	s_add_i32 s66, 0, 0x18000
	s_add_i32 s67, 0, 0x1c000
	v_add_u32_e32 v164, s66, v156
	v_add_u32_e32 v180, s67, v156
	ds_read_b128 v[144:147], v164
	ds_read_b128 v[148:151], v164 offset:1024
	ds_read_b128 v[152:155], v164 offset:2048
	ds_read_b128 v[164:167], v164 offset:3072
	ds_read_b128 v[168:171], v180
	ds_read_b128 v[172:175], v180 offset:1024
	ds_read_b128 v[176:179], v180 offset:2048
	ds_read_b128 v[180:183], v180 offset:3072
	s_add_u32 s8, s48, 0x160000
	s_addc_u32 s9, s49, 0
	s_mov_b32 m0, s55
	v_lshl_add_u64 v[184:185], s[8:9], 0, v[128:129]
	global_load_lds_dwordx4 v[184:185], off
	v_lshl_add_u64 v[184:185], s[8:9], 0, v[132:133]
	s_mov_b32 m0, s56
	s_nop 0
	global_load_lds_dwordx4 v[184:185], off
	ds_read_b128 v[184:187], v163 offset:32768
	ds_read_b128 v[188:191], v163 offset:33792
	ds_read_b128 v[192:195], v163 offset:34816
	ds_read_b128 v[196:199], v163 offset:35840
	ds_read_b128 v[200:203], v163 offset:36864
	ds_read_b128 v[204:207], v163 offset:37888
	ds_read_b128 v[208:211], v163 offset:38912
	ds_read_b128 v[212:215], v163 offset:39936
	s_waitcnt vmcnt(8)
	s_waitcnt lgkmcnt(0)
	s_barrier
	s_setprio 1
	s_waitcnt lgkmcnt(0)
	v_mfma_f32_16x16x32_bf16 v[124:127], v[144:147], v[184:187], v[124:127]
	v_mfma_f32_16x16x32_bf16 v[120:123], v[152:155], v[184:187], v[120:123]
	v_mfma_f32_16x16x32_bf16 v[108:111], v[144:147], v[192:195], v[108:111]
	v_mfma_f32_16x16x32_bf16 v[104:107], v[152:155], v[192:195], v[104:107]
	v_mfma_f32_16x16x32_bf16 v[92:95], v[144:147], v[200:203], v[92:95]
	v_mfma_f32_16x16x32_bf16 v[88:91], v[152:155], v[200:203], v[88:91]
	v_mfma_f32_16x16x32_bf16 v[76:79], v[144:147], v[208:211], v[76:79]
	v_mfma_f32_16x16x32_bf16 v[72:75], v[152:155], v[208:211], v[72:75]
	v_mfma_f32_16x16x32_bf16 v[124:127], v[148:151], v[188:191], v[124:127]
	v_mfma_f32_16x16x32_bf16 v[120:123], v[164:167], v[188:191], v[120:123]
	v_mfma_f32_16x16x32_bf16 v[108:111], v[148:151], v[196:199], v[108:111]
	v_mfma_f32_16x16x32_bf16 v[104:107], v[164:167], v[196:199], v[104:107]
	v_mfma_f32_16x16x32_bf16 v[92:95], v[148:151], v[204:207], v[92:95]
	v_mfma_f32_16x16x32_bf16 v[88:91], v[164:167], v[204:207], v[88:91]
	v_mfma_f32_16x16x32_bf16 v[76:79], v[148:151], v[212:215], v[76:79]
	v_mfma_f32_16x16x32_bf16 v[72:75], v[164:167], v[212:215], v[72:75]
	s_setprio 0
	s_setprio 1
	v_mfma_f32_16x16x32_bf16 v[116:119], v[168:171], v[184:187], v[116:119]
	v_mfma_f32_16x16x32_bf16 v[112:115], v[176:179], v[184:187], v[112:115]
	v_mfma_f32_16x16x32_bf16 v[100:103], v[168:171], v[192:195], v[100:103]
	v_mfma_f32_16x16x32_bf16 v[96:99], v[176:179], v[192:195], v[96:99]
	v_mfma_f32_16x16x32_bf16 v[84:87], v[168:171], v[200:203], v[84:87]
	v_mfma_f32_16x16x32_bf16 v[80:83], v[176:179], v[200:203], v[80:83]
	v_mfma_f32_16x16x32_bf16 v[68:71], v[168:171], v[208:211], v[68:71]
	v_mfma_f32_16x16x32_bf16 v[64:67], v[176:179], v[208:211], v[64:67]
	v_mfma_f32_16x16x32_bf16 v[116:119], v[172:175], v[188:191], v[116:119]
	v_mfma_f32_16x16x32_bf16 v[112:115], v[180:183], v[188:191], v[112:115]
	v_mfma_f32_16x16x32_bf16 v[100:103], v[172:175], v[196:199], v[100:103]
	v_mfma_f32_16x16x32_bf16 v[96:99], v[180:183], v[196:199], v[96:99]
	v_mfma_f32_16x16x32_bf16 v[84:87], v[172:175], v[204:207], v[84:87]
	v_mfma_f32_16x16x32_bf16 v[80:83], v[180:183], v[204:207], v[80:83]
	v_mfma_f32_16x16x32_bf16 v[68:71], v[172:175], v[212:215], v[68:71]
	v_mfma_f32_16x16x32_bf16 v[64:67], v[180:183], v[212:215], v[64:67]
	s_setprio 0
	s_barrier
	s_add_i32 s8, s66, s21
	v_lshl_add_u64 v[184:185], v[216:217], 0, s[36:37]
	s_mov_b32 m0, s8
	s_nop 0
	global_load_lds_dwordx4 v[184:185], off
	s_add_i32 m0, s8, 0x2000
	s_add_u32 s8, s46, 0x160080
	v_lshl_add_u64 v[184:185], v[218:219], 0, s[36:37]
	s_addc_u32 s9, s47, 0
	s_add_i32 s46, s67, s21
	global_load_lds_dwordx4 v[184:185], off
	ds_read_b128 v[184:187], v163 offset:49152
	ds_read_b128 v[188:191], v163 offset:50176
	ds_read_b128 v[192:195], v163 offset:51200
	ds_read_b128 v[196:199], v163 offset:52224
	ds_read_b128 v[200:203], v163 offset:53248
	ds_read_b128 v[204:207], v163 offset:54272
	ds_read_b128 v[208:211], v163 offset:55296
	ds_read_b128 v[212:215], v163 offset:56320
	s_waitcnt vmcnt(4)
	s_waitcnt lgkmcnt(0)
	s_barrier
	s_setprio 1
	s_waitcnt lgkmcnt(0)
	v_mfma_f32_16x16x32_bf16 v[60:63], v[144:147], v[184:187], v[60:63]
	v_mfma_f32_16x16x32_bf16 v[56:59], v[152:155], v[184:187], v[56:59]
	v_lshl_add_u64 v[228:229], s[8:9], 0, v[130:131]
	s_mov_b32 m0, s46
	s_nop 0
	global_load_lds_dwordx4 v[228:229], off
	v_mfma_f32_16x16x32_bf16 v[44:47], v[144:147], v[192:195], v[44:47]
	v_mfma_f32_16x16x32_bf16 v[40:43], v[152:155], v[192:195], v[40:43]
	v_mfma_f32_16x16x32_bf16 v[28:31], v[144:147], v[200:203], v[28:31]
	v_mfma_f32_16x16x32_bf16 v[24:27], v[152:155], v[200:203], v[24:27]
	v_lshl_add_u64 v[228:229], s[8:9], 0, v[134:135]
	s_add_i32 m0, s46, 0x2000
	s_nop 0
	global_load_lds_dwordx4 v[228:229], off
	v_mfma_f32_16x16x32_bf16 v[12:15], v[144:147], v[208:211], v[12:15]
	v_mfma_f32_16x16x32_bf16 v[8:11], v[152:155], v[208:211], v[8:11]
	v_mfma_f32_16x16x32_bf16 v[60:63], v[148:151], v[188:191], v[60:63]
	v_mfma_f32_16x16x32_bf16 v[56:59], v[164:167], v[188:191], v[56:59]
	v_lshl_add_u64 v[228:229], v[220:221], 0, s[36:37]
	s_mov_b32 m0, s26
	s_nop 0
	global_load_lds_dwordx4 v[228:229], off
	v_mfma_f32_16x16x32_bf16 v[44:47], v[148:151], v[196:199], v[44:47]
	v_mfma_f32_16x16x32_bf16 v[40:43], v[164:167], v[196:199], v[40:43]
	v_mfma_f32_16x16x32_bf16 v[28:31], v[148:151], v[204:207], v[28:31]
	v_mfma_f32_16x16x32_bf16 v[24:27], v[164:167], v[204:207], v[24:27]
	v_lshl_add_u64 v[228:229], v[222:223], 0, s[36:37]
	s_mov_b32 m0, s27
	s_nop 0
	global_load_lds_dwordx4 v[228:229], off
	v_mfma_f32_16x16x32_bf16 v[12:15], v[148:151], v[212:215], v[12:15]
	v_mfma_f32_16x16x32_bf16 v[8:11], v[164:167], v[212:215], v[8:11]
	s_setprio 0
	s_setprio 1
	v_mfma_f32_16x16x32_bf16 v[52:55], v[168:171], v[184:187], v[52:55]
	v_mfma_f32_16x16x32_bf16 v[48:51], v[176:179], v[184:187], v[48:51]
	v_mfma_f32_16x16x32_bf16 v[36:39], v[168:171], v[192:195], v[36:39]
	v_mfma_f32_16x16x32_bf16 v[32:35], v[176:179], v[192:195], v[32:35]
	v_mfma_f32_16x16x32_bf16 v[20:23], v[168:171], v[200:203], v[20:23]
	v_mfma_f32_16x16x32_bf16 v[16:19], v[176:179], v[200:203], v[16:19]
	v_mfma_f32_16x16x32_bf16 v[4:7], v[168:171], v[208:211], v[4:7]
	v_mfma_f32_16x16x32_bf16 v[0:3], v[176:179], v[208:211], v[0:3]
	v_mfma_f32_16x16x32_bf16 v[52:55], v[172:175], v[188:191], v[52:55]
	v_mfma_f32_16x16x32_bf16 v[48:51], v[180:183], v[188:191], v[48:51]
	v_mfma_f32_16x16x32_bf16 v[36:39], v[172:175], v[196:199], v[36:39]
	v_mfma_f32_16x16x32_bf16 v[32:35], v[180:183], v[196:199], v[32:35]
	v_mfma_f32_16x16x32_bf16 v[20:23], v[172:175], v[204:207], v[20:23]
	v_mfma_f32_16x16x32_bf16 v[16:19], v[180:183], v[204:207], v[16:19]
	v_mfma_f32_16x16x32_bf16 v[4:7], v[172:175], v[212:215], v[4:7]
	v_mfma_f32_16x16x32_bf16 v[0:3], v[180:183], v[212:215], v[0:3]
	s_setprio 0
	s_barrier
	s_add_i32 s65, s65, 2
	s_add_u32 s63, s63, 0x100
	s_addc_u32 s64, s64, 0
	s_cmpk_gt_u32 s65, 0x55
	s_mov_b64 s[8:9], s[6:7]
	s_cbranch_scc0 .LBB0_248
	s_and_b64 vcc, exec, s[28:29]
	s_cbranch_vccz .LBB0_251
	s_barrier

.LBB0_387:
	ds_read_b128 v[146:149], v156
	ds_read_b128 v[160:163], v156 offset:1024
	ds_read_b128 v[164:167], v156 offset:2048
	ds_read_b128 v[168:171], v156 offset:3072
	ds_read_b128 v[172:175], v157
	ds_read_b128 v[176:179], v157 offset:1024
	ds_read_b128 v[180:183], v157 offset:2048
	ds_read_b128 v[184:187], v157 offset:3072
	s_add_u32 s38, s36, 0x100
	s_addc_u32 s39, s37, 0
	s_cmp_eq_u32 s64, 28
	s_cselect_b32 s43, s29, s39
	s_cselect_b32 s42, s60, s38
	s_cselect_b32 s41, s19, s63
	s_cselect_b32 s40, s61, s62
	v_lshl_add_u64 v[150:151], s[36:37], 0, v[138:139]
	s_add_i32 m0, s46, 0xc000
	s_nop 0
	global_load_lds_dwordx4 v[150:151], off
	v_lshl_add_u64 v[150:151], s[36:37], 0, v[140:141]
	s_add_i32 m0, s46, 0xe000
	s_nop 0
	global_load_lds_dwordx4 v[150:151], off
	ds_read_b128 v[188:191], v158
	ds_read_b128 v[192:195], v158 offset:1024
	ds_read_b128 v[196:199], v158 offset:2048
	ds_read_b128 v[200:203], v158 offset:3072
	ds_read_b128 v[204:207], v158 offset:4096
	ds_read_b128 v[208:211], v158 offset:5120
	ds_read_b128 v[212:215], v158 offset:6144
	ds_read_b128 v[216:219], v158 offset:7168
	s_waitcnt vmcnt(8)
	s_waitcnt lgkmcnt(0)
	s_barrier
	s_setprio 1
	s_waitcnt lgkmcnt(0)
	v_mfma_f32_16x16x32_bf16 v[124:127], v[146:149], v[188:191], v[124:127]
	v_mfma_f32_16x16x32_bf16 v[120:123], v[164:167], v[188:191], v[120:123]
	v_mfma_f32_16x16x32_bf16 v[108:111], v[146:149], v[196:199], v[108:111]
	v_mfma_f32_16x16x32_bf16 v[104:107], v[164:167], v[196:199], v[104:107]
	v_mfma_f32_16x16x32_bf16 v[92:95], v[146:149], v[204:207], v[92:95]
	v_mfma_f32_16x16x32_bf16 v[88:91], v[164:167], v[204:207], v[88:91]
	v_mfma_f32_16x16x32_bf16 v[76:79], v[146:149], v[212:215], v[76:79]
	v_mfma_f32_16x16x32_bf16 v[72:75], v[164:167], v[212:215], v[72:75]
	v_mfma_f32_16x16x32_bf16 v[124:127], v[160:163], v[192:195], v[124:127]
	v_mfma_f32_16x16x32_bf16 v[120:123], v[168:171], v[192:195], v[120:123]
	v_mfma_f32_16x16x32_bf16 v[108:111], v[160:163], v[200:203], v[108:111]
	v_mfma_f32_16x16x32_bf16 v[104:107], v[168:171], v[200:203], v[104:107]
	v_mfma_f32_16x16x32_bf16 v[92:95], v[160:163], v[208:211], v[92:95]
	v_mfma_f32_16x16x32_bf16 v[88:91], v[168:171], v[208:211], v[88:91]
	v_mfma_f32_16x16x32_bf16 v[76:79], v[160:163], v[216:219], v[76:79]
	v_mfma_f32_16x16x32_bf16 v[72:75], v[168:171], v[216:219], v[72:75]
	s_setprio 0
	s_setprio 1
	v_mfma_f32_16x16x32_bf16 v[116:119], v[172:175], v[188:191], v[116:119]
	v_mfma_f32_16x16x32_bf16 v[112:115], v[180:183], v[188:191], v[112:115]
	v_mfma_f32_16x16x32_bf16 v[100:103], v[172:175], v[196:199], v[100:103]
	v_mfma_f32_16x16x32_bf16 v[96:99], v[180:183], v[196:199], v[96:99]
	v_mfma_f32_16x16x32_bf16 v[84:87], v[172:175], v[204:207], v[84:87]
	v_mfma_f32_16x16x32_bf16 v[80:83], v[180:183], v[204:207], v[80:83]
	v_mfma_f32_16x16x32_bf16 v[68:71], v[172:175], v[212:215], v[68:71]
	v_mfma_f32_16x16x32_bf16 v[64:67], v[180:183], v[212:215], v[64:67]
	v_mfma_f32_16x16x32_bf16 v[116:119], v[176:179], v[192:195], v[116:119]
	v_mfma_f32_16x16x32_bf16 v[112:115], v[184:187], v[192:195], v[112:115]
	v_mfma_f32_16x16x32_bf16 v[100:103], v[176:179], v[200:203], v[100:103]
	v_mfma_f32_16x16x32_bf16 v[96:99], v[184:187], v[200:203], v[96:99]
	v_mfma_f32_16x16x32_bf16 v[84:87], v[176:179], v[208:211], v[84:87]
	v_mfma_f32_16x16x32_bf16 v[80:83], v[184:187], v[208:211], v[80:83]
	v_mfma_f32_16x16x32_bf16 v[68:71], v[176:179], v[216:219], v[68:71]
	v_mfma_f32_16x16x32_bf16 v[64:67], v[184:187], v[216:219], v[64:67]
	s_setprio 0
	s_barrier
	s_add_i32 s36, s55, s11
	v_lshl_add_u64 v[150:151], s[40:41], 0, v[130:131]
	s_mov_b32 m0, s36
	v_lshl_add_u64 v[220:221], s[40:41], 0, v[134:135]
	global_load_lds_dwordx4 v[150:151], off
	s_add_i32 m0, s36, 0x2000
	s_add_u32 s36, s40, 0x80000
	s_addc_u32 s37, s41, 0
	s_add_i32 s65, s56, s11
	global_load_lds_dwordx4 v[220:221], off
	v_lshl_add_u64 v[222:223], s[42:43], 0, v[128:129]
	v_lshl_add_u64 v[224:225], s[42:43], 0, v[132:133]
	ds_read_b128 v[188:191], v158 offset:16384
	ds_read_b128 v[192:195], v158 offset:17408
	ds_read_b128 v[196:199], v158 offset:18432
	ds_read_b128 v[200:203], v158 offset:19456
	ds_read_b128 v[204:207], v158 offset:20480
	ds_read_b128 v[208:211], v158 offset:21504
	ds_read_b128 v[212:215], v158 offset:22528
	ds_read_b128 v[216:219], v158 offset:23552
	s_waitcnt vmcnt(4)
	s_waitcnt lgkmcnt(0)
	s_barrier
	s_setprio 1
	s_waitcnt lgkmcnt(0)
	v_mfma_f32_16x16x32_bf16 v[60:63], v[146:149], v[188:191], v[60:63]
	v_mfma_f32_16x16x32_bf16 v[56:59], v[164:167], v[188:191], v[56:59]
	v_lshl_add_u64 v[228:229], s[36:37], 0, v[130:131]
	s_mov_b32 m0, s65
	s_nop 0
	global_load_lds_dwordx4 v[228:229], off
	v_mfma_f32_16x16x32_bf16 v[44:47], v[146:149], v[196:199], v[44:47]
	v_mfma_f32_16x16x32_bf16 v[40:43], v[164:167], v[196:199], v[40:43]
	v_mfma_f32_16x16x32_bf16 v[28:31], v[146:149], v[204:207], v[28:31]
	v_mfma_f32_16x16x32_bf16 v[24:27], v[164:167], v[204:207], v[24:27]
	v_lshl_add_u64 v[228:229], s[36:37], 0, v[134:135]
	s_add_i32 m0, s65, 0x2000
	s_nop 0
	global_load_lds_dwordx4 v[228:229], off
	v_mfma_f32_16x16x32_bf16 v[12:15], v[146:149], v[212:215], v[12:15]
	v_mfma_f32_16x16x32_bf16 v[8:11], v[164:167], v[212:215], v[8:11]
	v_mfma_f32_16x16x32_bf16 v[60:63], v[160:163], v[192:195], v[60:63]
	v_mfma_f32_16x16x32_bf16 v[56:59], v[168:171], v[192:195], v[56:59]
	s_mov_b32 m0, s46
	s_nop 0
	global_load_lds_dwordx4 v[222:223], off
	v_mfma_f32_16x16x32_bf16 v[44:47], v[160:163], v[200:203], v[44:47]
	v_mfma_f32_16x16x32_bf16 v[40:43], v[168:171], v[200:203], v[40:43]
	v_mfma_f32_16x16x32_bf16 v[28:31], v[160:163], v[208:211], v[28:31]
	v_mfma_f32_16x16x32_bf16 v[24:27], v[168:171], v[208:211], v[24:27]
	s_mov_b32 m0, s47
	s_nop 0
	global_load_lds_dwordx4 v[224:225], off
	v_mfma_f32_16x16x32_bf16 v[12:15], v[160:163], v[216:219], v[12:15]
	v_mfma_f32_16x16x32_bf16 v[8:11], v[168:171], v[216:219], v[8:11]
	s_setprio 0
	s_setprio 1
	v_mfma_f32_16x16x32_bf16 v[52:55], v[172:175], v[188:191], v[52:55]
	v_mfma_f32_16x16x32_bf16 v[48:51], v[180:183], v[188:191], v[48:51]
	v_mfma_f32_16x16x32_bf16 v[36:39], v[172:175], v[196:199], v[36:39]
	v_mfma_f32_16x16x32_bf16 v[32:35], v[180:183], v[196:199], v[32:35]
	v_mfma_f32_16x16x32_bf16 v[20:23], v[172:175], v[204:207], v[20:23]
	v_mfma_f32_16x16x32_bf16 v[16:19], v[180:183], v[204:207], v[16:19]
	v_mfma_f32_16x16x32_bf16 v[4:7], v[172:175], v[212:215], v[4:7]
	v_mfma_f32_16x16x32_bf16 v[0:3], v[180:183], v[212:215], v[0:3]
	v_mfma_f32_16x16x32_bf16 v[52:55], v[176:179], v[192:195], v[52:55]
	v_mfma_f32_16x16x32_bf16 v[48:51], v[184:187], v[192:195], v[48:51]
	v_mfma_f32_16x16x32_bf16 v[36:39], v[176:179], v[200:203], v[36:39]
	v_mfma_f32_16x16x32_bf16 v[32:35], v[184:187], v[200:203], v[32:35]
	v_mfma_f32_16x16x32_bf16 v[20:23], v[176:179], v[208:211], v[20:23]
	v_mfma_f32_16x16x32_bf16 v[16:19], v[184:187], v[208:211], v[16:19]
	v_mfma_f32_16x16x32_bf16 v[4:7], v[176:179], v[216:219], v[4:7]
	v_mfma_f32_16x16x32_bf16 v[0:3], v[184:187], v[216:219], v[0:3]
	s_setprio 0
	s_barrier
	s_add_i32 s65, 0, 0x18000
	s_add_i32 s66, 0, 0x1c000
	v_add_u32_e32 v168, s65, v154
	v_add_u32_e32 v184, s66, v154
	ds_read_b128 v[146:149], v168
	ds_read_b128 v[160:163], v168 offset:1024
	ds_read_b128 v[164:167], v168 offset:2048
	ds_read_b128 v[168:171], v168 offset:3072
	ds_read_b128 v[172:175], v184
	ds_read_b128 v[176:179], v184 offset:1024
	ds_read_b128 v[180:183], v184 offset:2048
	ds_read_b128 v[184:187], v184 offset:3072
	s_add_u32 s36, s42, 0x80000
	s_addc_u32 s37, s43, 0
	s_mov_b32 m0, s48
	v_lshl_add_u64 v[188:189], s[36:37], 0, v[128:129]
	global_load_lds_dwordx4 v[188:189], off
	v_lshl_add_u64 v[188:189], s[36:37], 0, v[132:133]
	s_mov_b32 m0, s49
	s_nop 0
	global_load_lds_dwordx4 v[188:189], off
	ds_read_b128 v[188:191], v158 offset:32768
	ds_read_b128 v[192:195], v158 offset:33792
	ds_read_b128 v[196:199], v158 offset:34816
	ds_read_b128 v[200:203], v158 offset:35840
	ds_read_b128 v[204:207], v158 offset:36864
	ds_read_b128 v[208:211], v158 offset:37888
	ds_read_b128 v[212:215], v158 offset:38912
	ds_read_b128 v[216:219], v158 offset:39936
	s_waitcnt vmcnt(8)
	s_waitcnt lgkmcnt(0)
	s_barrier
	s_setprio 1
	s_waitcnt lgkmcnt(0)
	v_mfma_f32_16x16x32_bf16 v[124:127], v[146:149], v[188:191], v[124:127]
	v_mfma_f32_16x16x32_bf16 v[120:123], v[164:167], v[188:191], v[120:123]
	v_mfma_f32_16x16x32_bf16 v[108:111], v[146:149], v[196:199], v[108:111]
	v_mfma_f32_16x16x32_bf16 v[104:107], v[164:167], v[196:199], v[104:107]
	v_mfma_f32_16x16x32_bf16 v[92:95], v[146:149], v[204:207], v[92:95]
	v_mfma_f32_16x16x32_bf16 v[88:91], v[164:167], v[204:207], v[88:91]
	v_mfma_f32_16x16x32_bf16 v[76:79], v[146:149], v[212:215], v[76:79]
	v_mfma_f32_16x16x32_bf16 v[72:75], v[164:167], v[212:215], v[72:75]
	v_mfma_f32_16x16x32_bf16 v[124:127], v[160:163], v[192:195], v[124:127]
	v_mfma_f32_16x16x32_bf16 v[120:123], v[168:171], v[192:195], v[120:123]
	v_mfma_f32_16x16x32_bf16 v[108:111], v[160:163], v[200:203], v[108:111]
	v_mfma_f32_16x16x32_bf16 v[104:107], v[168:171], v[200:203], v[104:107]
	v_mfma_f32_16x16x32_bf16 v[92:95], v[160:163], v[208:211], v[92:95]
	v_mfma_f32_16x16x32_bf16 v[88:91], v[168:171], v[208:211], v[88:91]
	v_mfma_f32_16x16x32_bf16 v[76:79], v[160:163], v[216:219], v[76:79]
	v_mfma_f32_16x16x32_bf16 v[72:75], v[168:171], v[216:219], v[72:75]
	s_setprio 0
	s_setprio 1
	v_mfma_f32_16x16x32_bf16 v[116:119], v[172:175], v[188:191], v[116:119]
	v_mfma_f32_16x16x32_bf16 v[112:115], v[180:183], v[188:191], v[112:115]
	v_mfma_f32_16x16x32_bf16 v[100:103], v[172:175], v[196:199], v[100:103]
	v_mfma_f32_16x16x32_bf16 v[96:99], v[180:183], v[196:199], v[96:99]
	v_mfma_f32_16x16x32_bf16 v[84:87], v[172:175], v[204:207], v[84:87]
	v_mfma_f32_16x16x32_bf16 v[80:83], v[180:183], v[204:207], v[80:83]
	v_mfma_f32_16x16x32_bf16 v[68:71], v[172:175], v[212:215], v[68:71]
	v_mfma_f32_16x16x32_bf16 v[64:67], v[180:183], v[212:215], v[64:67]
	v_mfma_f32_16x16x32_bf16 v[116:119], v[176:179], v[192:195], v[116:119]
	v_mfma_f32_16x16x32_bf16 v[112:115], v[184:187], v[192:195], v[112:115]
	v_mfma_f32_16x16x32_bf16 v[100:103], v[176:179], v[200:203], v[100:103]
	v_mfma_f32_16x16x32_bf16 v[96:99], v[184:187], v[200:203], v[96:99]
	v_mfma_f32_16x16x32_bf16 v[84:87], v[176:179], v[208:211], v[84:87]
	v_mfma_f32_16x16x32_bf16 v[80:83], v[184:187], v[208:211], v[80:83]
	v_mfma_f32_16x16x32_bf16 v[68:71], v[176:179], v[216:219], v[68:71]
	v_mfma_f32_16x16x32_bf16 v[64:67], v[184:187], v[216:219], v[64:67]
	s_setprio 0
	s_barrier
	s_add_i32 s36, s65, s11
	v_lshl_add_u64 v[150:151], v[150:151], 0, s[14:15]
	s_mov_b32 m0, s36
	s_nop 0
	global_load_lds_dwordx4 v[150:151], off
	s_add_i32 m0, s36, 0x2000
	s_add_u32 s36, s40, 0x80080
	v_lshl_add_u64 v[150:151], v[220:221], 0, s[14:15]
	s_addc_u32 s37, s41, 0
	s_add_i32 s40, s66, s11
	global_load_lds_dwordx4 v[150:151], off
	v_lshl_add_u64 v[150:151], v[224:225], 0, s[14:15]
	ds_read_b128 v[188:191], v158 offset:49152
	ds_read_b128 v[192:195], v158 offset:50176
	ds_read_b128 v[196:199], v158 offset:51200
	ds_read_b128 v[200:203], v158 offset:52224
	ds_read_b128 v[204:207], v158 offset:53248
	ds_read_b128 v[208:211], v158 offset:54272
	ds_read_b128 v[212:215], v158 offset:55296
	ds_read_b128 v[216:219], v158 offset:56320
	s_waitcnt vmcnt(4)
	s_waitcnt lgkmcnt(0)
	s_barrier
	s_setprio 1
	s_waitcnt lgkmcnt(0)
	v_mfma_f32_16x16x32_bf16 v[60:63], v[146:149], v[188:191], v[60:63]
	v_mfma_f32_16x16x32_bf16 v[56:59], v[164:167], v[188:191], v[56:59]
	v_lshl_add_u64 v[228:229], s[36:37], 0, v[130:131]
	s_mov_b32 m0, s40
	s_nop 0
	global_load_lds_dwordx4 v[228:229], off
	v_mfma_f32_16x16x32_bf16 v[44:47], v[146:149], v[196:199], v[44:47]
	v_mfma_f32_16x16x32_bf16 v[40:43], v[164:167], v[196:199], v[40:43]
	v_mfma_f32_16x16x32_bf16 v[28:31], v[146:149], v[204:207], v[28:31]
	v_mfma_f32_16x16x32_bf16 v[24:27], v[164:167], v[204:207], v[24:27]
	v_lshl_add_u64 v[228:229], s[36:37], 0, v[134:135]
	s_add_i32 m0, s40, 0x2000
	s_nop 0
	global_load_lds_dwordx4 v[228:229], off
	v_mfma_f32_16x16x32_bf16 v[12:15], v[146:149], v[212:215], v[12:15]
	v_mfma_f32_16x16x32_bf16 v[8:11], v[164:167], v[212:215], v[8:11]
	v_mfma_f32_16x16x32_bf16 v[60:63], v[160:163], v[192:195], v[60:63]
	v_mfma_f32_16x16x32_bf16 v[56:59], v[168:171], v[192:195], v[56:59]
	v_lshl_add_u64 v[228:229], v[222:223], 0, s[14:15]
	s_mov_b32 m0, s53
	s_nop 0
	global_load_lds_dwordx4 v[228:229], off
	v_mfma_f32_16x16x32_bf16 v[44:47], v[160:163], v[200:203], v[44:47]
	v_mfma_f32_16x16x32_bf16 v[40:43], v[168:171], v[200:203], v[40:43]
	v_mfma_f32_16x16x32_bf16 v[28:31], v[160:163], v[208:211], v[28:31]
	v_mfma_f32_16x16x32_bf16 v[24:27], v[168:171], v[208:211], v[24:27]
	s_mov_b32 m0, s54
	s_nop 0
	global_load_lds_dwordx4 v[150:151], off
	v_mfma_f32_16x16x32_bf16 v[12:15], v[160:163], v[216:219], v[12:15]
	v_mfma_f32_16x16x32_bf16 v[8:11], v[168:171], v[216:219], v[8:11]
	s_setprio 0
	s_setprio 1
	v_mfma_f32_16x16x32_bf16 v[52:55], v[172:175], v[188:191], v[52:55]
	v_mfma_f32_16x16x32_bf16 v[48:51], v[180:183], v[188:191], v[48:51]
	v_mfma_f32_16x16x32_bf16 v[36:39], v[172:175], v[196:199], v[36:39]
	v_mfma_f32_16x16x32_bf16 v[32:35], v[180:183], v[196:199], v[32:35]
	v_mfma_f32_16x16x32_bf16 v[20:23], v[172:175], v[204:207], v[20:23]
	v_mfma_f32_16x16x32_bf16 v[16:19], v[180:183], v[204:207], v[16:19]
	v_mfma_f32_16x16x32_bf16 v[4:7], v[172:175], v[212:215], v[4:7]
	v_mfma_f32_16x16x32_bf16 v[0:3], v[180:183], v[212:215], v[0:3]
	v_mfma_f32_16x16x32_bf16 v[52:55], v[176:179], v[192:195], v[52:55]
	v_mfma_f32_16x16x32_bf16 v[48:51], v[184:187], v[192:195], v[48:51]
	v_mfma_f32_16x16x32_bf16 v[36:39], v[176:179], v[200:203], v[36:39]
	v_mfma_f32_16x16x32_bf16 v[32:35], v[184:187], v[200:203], v[32:35]
	v_mfma_f32_16x16x32_bf16 v[20:23], v[176:179], v[208:211], v[20:23]
	v_mfma_f32_16x16x32_bf16 v[16:19], v[184:187], v[208:211], v[16:19]
	v_mfma_f32_16x16x32_bf16 v[4:7], v[176:179], v[216:219], v[4:7]
	v_mfma_f32_16x16x32_bf16 v[0:3], v[184:187], v[216:219], v[0:3]
	s_setprio 0
	s_barrier
	s_add_i32 s64, s64, 2
	s_add_u32 s62, s62, 0x100
	s_addc_u32 s63, s63, 0
	s_cmp_gt_u32 s64, 29
	s_mov_b64 s[36:37], s[38:39]
	s_cbranch_scc0 .LBB0_387
	s_and_b64 vcc, exec, s[4:5]
	s_cbranch_vccnz .LBB0_392
	s_cmp_gt_i32 s59, 11
	s_mov_b64 s[36:37], -1
	s_cbranch_scc1 .LBB0_393

.LBB0_1117:
	ds_read_b128 v[144:147], v159
	ds_read_b128 v[148:151], v159 offset:1024
	ds_read_b128 v[162:165], v159 offset:2048
	ds_read_b128 v[166:169], v159 offset:3072
	ds_read_b128 v[170:173], v160
	ds_read_b128 v[174:177], v160 offset:1024
	ds_read_b128 v[178:181], v160 offset:2048
	ds_read_b128 v[182:185], v160 offset:3072
	s_add_u32 s48, s46, 0xfff80080
	s_addc_u32 s49, s47, -1
	s_cmp_eq_u32 s63, 28
	s_cselect_b32 s51, s7, s49
	s_cselect_b32 s50, s11, s48
	s_cselect_b32 s49, s37, s62
	s_cselect_b32 s48, s39, s45
	v_lshl_add_u64 v[152:153], s[46:47], 0, v[136:137]
	s_add_i32 m0, s55, 0xc000
	s_nop 0
	global_load_lds_dwordx4 v[152:153], off
	v_lshl_add_u64 v[152:153], s[46:47], 0, v[138:139]
	s_add_i32 m0, s55, 0xe000
	s_nop 0
	global_load_lds_dwordx4 v[152:153], off
	ds_read_b128 v[186:189], v161
	ds_read_b128 v[190:193], v161 offset:1024
	ds_read_b128 v[194:197], v161 offset:2048
	ds_read_b128 v[198:201], v161 offset:3072
	ds_read_b128 v[202:205], v161 offset:4096
	ds_read_b128 v[206:209], v161 offset:5120
	ds_read_b128 v[210:213], v161 offset:6144
	ds_read_b128 v[214:217], v161 offset:7168
	s_waitcnt vmcnt(8)
	s_waitcnt lgkmcnt(0)
	s_barrier
	s_setprio 1
	s_waitcnt lgkmcnt(0)
	v_mfma_f32_16x16x32_bf16 v[124:127], v[144:147], v[186:189], v[124:127]
	v_mfma_f32_16x16x32_bf16 v[120:123], v[162:165], v[186:189], v[120:123]
	v_mfma_f32_16x16x32_bf16 v[108:111], v[144:147], v[194:197], v[108:111]
	v_mfma_f32_16x16x32_bf16 v[104:107], v[162:165], v[194:197], v[104:107]
	v_mfma_f32_16x16x32_bf16 v[92:95], v[144:147], v[202:205], v[92:95]
	v_mfma_f32_16x16x32_bf16 v[88:91], v[162:165], v[202:205], v[88:91]
	v_mfma_f32_16x16x32_bf16 v[76:79], v[144:147], v[210:213], v[76:79]
	v_mfma_f32_16x16x32_bf16 v[72:75], v[162:165], v[210:213], v[72:75]
	v_mfma_f32_16x16x32_bf16 v[124:127], v[148:151], v[190:193], v[124:127]
	v_mfma_f32_16x16x32_bf16 v[120:123], v[166:169], v[190:193], v[120:123]
	v_mfma_f32_16x16x32_bf16 v[108:111], v[148:151], v[198:201], v[108:111]
	v_mfma_f32_16x16x32_bf16 v[104:107], v[166:169], v[198:201], v[104:107]
	v_mfma_f32_16x16x32_bf16 v[92:95], v[148:151], v[206:209], v[92:95]
	v_mfma_f32_16x16x32_bf16 v[88:91], v[166:169], v[206:209], v[88:91]
	v_mfma_f32_16x16x32_bf16 v[76:79], v[148:151], v[214:217], v[76:79]
	v_mfma_f32_16x16x32_bf16 v[72:75], v[166:169], v[214:217], v[72:75]
	s_setprio 0
	s_setprio 1
	v_mfma_f32_16x16x32_bf16 v[116:119], v[170:173], v[186:189], v[116:119]
	v_mfma_f32_16x16x32_bf16 v[112:115], v[178:181], v[186:189], v[112:115]
	v_mfma_f32_16x16x32_bf16 v[100:103], v[170:173], v[194:197], v[100:103]
	v_mfma_f32_16x16x32_bf16 v[96:99], v[178:181], v[194:197], v[96:99]
	v_mfma_f32_16x16x32_bf16 v[84:87], v[170:173], v[202:205], v[84:87]
	v_mfma_f32_16x16x32_bf16 v[80:83], v[178:181], v[202:205], v[80:83]
	v_mfma_f32_16x16x32_bf16 v[68:71], v[170:173], v[210:213], v[68:71]
	v_mfma_f32_16x16x32_bf16 v[64:67], v[178:181], v[210:213], v[64:67]
	v_mfma_f32_16x16x32_bf16 v[116:119], v[174:177], v[190:193], v[116:119]
	v_mfma_f32_16x16x32_bf16 v[112:115], v[182:185], v[190:193], v[112:115]
	v_mfma_f32_16x16x32_bf16 v[100:103], v[174:177], v[198:201], v[100:103]
	v_mfma_f32_16x16x32_bf16 v[96:99], v[182:185], v[198:201], v[96:99]
	v_mfma_f32_16x16x32_bf16 v[84:87], v[174:177], v[206:209], v[84:87]
	v_mfma_f32_16x16x32_bf16 v[80:83], v[182:185], v[206:209], v[80:83]
	v_mfma_f32_16x16x32_bf16 v[68:71], v[174:177], v[214:217], v[68:71]
	v_mfma_f32_16x16x32_bf16 v[64:67], v[182:185], v[214:217], v[64:67]
	s_setprio 0
	s_barrier
	s_add_i32 s64, s60, s21
	v_lshl_add_u64 v[152:153], s[48:49], 0, v[130:131]
	s_mov_b32 m0, s64
	v_lshl_add_u64 v[218:219], s[48:49], 0, v[134:135]
	global_load_lds_dwordx4 v[152:153], off
	s_add_i32 m0, s64, 0x2000
	s_add_u32 s64, s48, 0x80000
	s_addc_u32 s65, s49, 0
	s_add_i32 s66, s61, s21
	global_load_lds_dwordx4 v[218:219], off
	v_lshl_add_u64 v[220:221], s[50:51], 0, v[128:129]
	v_lshl_add_u64 v[222:223], s[50:51], 0, v[132:133]
	ds_read_b128 v[186:189], v161 offset:16384
	ds_read_b128 v[190:193], v161 offset:17408
	ds_read_b128 v[194:197], v161 offset:18432
	ds_read_b128 v[198:201], v161 offset:19456
	ds_read_b128 v[202:205], v161 offset:20480
	ds_read_b128 v[206:209], v161 offset:21504
	ds_read_b128 v[210:213], v161 offset:22528
	ds_read_b128 v[214:217], v161 offset:23552
	s_waitcnt vmcnt(4)
	s_waitcnt lgkmcnt(0)
	s_barrier
	s_setprio 1
	s_waitcnt lgkmcnt(0)
	v_mfma_f32_16x16x32_bf16 v[60:63], v[144:147], v[186:189], v[60:63]
	v_mfma_f32_16x16x32_bf16 v[56:59], v[162:165], v[186:189], v[56:59]
	v_lshl_add_u64 v[228:229], s[64:65], 0, v[130:131]
	s_mov_b32 m0, s66
	s_nop 0
	global_load_lds_dwordx4 v[228:229], off
	v_mfma_f32_16x16x32_bf16 v[44:47], v[144:147], v[194:197], v[44:47]
	v_mfma_f32_16x16x32_bf16 v[40:43], v[162:165], v[194:197], v[40:43]
	v_mfma_f32_16x16x32_bf16 v[28:31], v[144:147], v[202:205], v[28:31]
	v_mfma_f32_16x16x32_bf16 v[24:27], v[162:165], v[202:205], v[24:27]
	v_lshl_add_u64 v[228:229], s[64:65], 0, v[134:135]
	s_add_i32 m0, s66, 0x2000
	s_nop 0
	global_load_lds_dwordx4 v[228:229], off
	v_mfma_f32_16x16x32_bf16 v[12:15], v[144:147], v[210:213], v[12:15]
	v_mfma_f32_16x16x32_bf16 v[8:11], v[162:165], v[210:213], v[8:11]
	v_mfma_f32_16x16x32_bf16 v[60:63], v[148:151], v[190:193], v[60:63]
	v_mfma_f32_16x16x32_bf16 v[56:59], v[166:169], v[190:193], v[56:59]
	s_mov_b32 m0, s55
	s_nop 0
	global_load_lds_dwordx4 v[220:221], off
	v_mfma_f32_16x16x32_bf16 v[44:47], v[148:151], v[198:201], v[44:47]
	v_mfma_f32_16x16x32_bf16 v[40:43], v[166:169], v[198:201], v[40:43]
	v_mfma_f32_16x16x32_bf16 v[28:31], v[148:151], v[206:209], v[28:31]
	v_mfma_f32_16x16x32_bf16 v[24:27], v[166:169], v[206:209], v[24:27]
	s_mov_b32 m0, s56
	s_nop 0
	global_load_lds_dwordx4 v[222:223], off
	v_mfma_f32_16x16x32_bf16 v[12:15], v[148:151], v[214:217], v[12:15]
	v_mfma_f32_16x16x32_bf16 v[8:11], v[166:169], v[214:217], v[8:11]
	s_setprio 0
	s_setprio 1
	v_mfma_f32_16x16x32_bf16 v[52:55], v[170:173], v[186:189], v[52:55]
	v_mfma_f32_16x16x32_bf16 v[48:51], v[178:181], v[186:189], v[48:51]
	v_mfma_f32_16x16x32_bf16 v[36:39], v[170:173], v[194:197], v[36:39]
	v_mfma_f32_16x16x32_bf16 v[32:35], v[178:181], v[194:197], v[32:35]
	v_mfma_f32_16x16x32_bf16 v[20:23], v[170:173], v[202:205], v[20:23]
	v_mfma_f32_16x16x32_bf16 v[16:19], v[178:181], v[202:205], v[16:19]
	v_mfma_f32_16x16x32_bf16 v[4:7], v[170:173], v[210:213], v[4:7]
	v_mfma_f32_16x16x32_bf16 v[0:3], v[178:181], v[210:213], v[0:3]
	v_mfma_f32_16x16x32_bf16 v[52:55], v[174:177], v[190:193], v[52:55]
	v_mfma_f32_16x16x32_bf16 v[48:51], v[182:185], v[190:193], v[48:51]
	v_mfma_f32_16x16x32_bf16 v[36:39], v[174:177], v[198:201], v[36:39]
	v_mfma_f32_16x16x32_bf16 v[32:35], v[182:185], v[198:201], v[32:35]
	v_mfma_f32_16x16x32_bf16 v[20:23], v[174:177], v[206:209], v[20:23]
	v_mfma_f32_16x16x32_bf16 v[16:19], v[182:185], v[206:209], v[16:19]
	v_mfma_f32_16x16x32_bf16 v[4:7], v[174:177], v[214:217], v[4:7]
	v_mfma_f32_16x16x32_bf16 v[0:3], v[182:185], v[214:217], v[0:3]
	s_setprio 0
	s_barrier
	s_add_i32 s64, 0, 0x18000
	s_add_i32 s65, 0, 0x1c000
	v_add_u32_e32 v166, s64, v154
	v_add_u32_e32 v182, s65, v154
	ds_read_b128 v[144:147], v166
	ds_read_b128 v[148:151], v166 offset:1024
	ds_read_b128 v[162:165], v166 offset:2048
	ds_read_b128 v[166:169], v166 offset:3072
	ds_read_b128 v[170:173], v182
	ds_read_b128 v[174:177], v182 offset:1024
	ds_read_b128 v[178:181], v182 offset:2048
	ds_read_b128 v[182:185], v182 offset:3072
	s_add_u32 s50, s50, 0x80000
	s_addc_u32 s51, s51, 0
	s_mov_b32 m0, s57
	v_lshl_add_u64 v[186:187], s[50:51], 0, v[128:129]
	global_load_lds_dwordx4 v[186:187], off
	v_lshl_add_u64 v[186:187], s[50:51], 0, v[132:133]
	s_mov_b32 m0, s58
	s_nop 0
	global_load_lds_dwordx4 v[186:187], off
	ds_read_b128 v[186:189], v161 offset:32768
	ds_read_b128 v[190:193], v161 offset:33792
	ds_read_b128 v[194:197], v161 offset:34816
	ds_read_b128 v[198:201], v161 offset:35840
	ds_read_b128 v[202:205], v161 offset:36864
	ds_read_b128 v[206:209], v161 offset:37888
	ds_read_b128 v[210:213], v161 offset:38912
	ds_read_b128 v[214:217], v161 offset:39936
	s_waitcnt vmcnt(8)
	s_waitcnt lgkmcnt(0)
	s_barrier
	s_setprio 1
	s_waitcnt lgkmcnt(0)
	v_mfma_f32_16x16x32_bf16 v[124:127], v[144:147], v[186:189], v[124:127]
	v_mfma_f32_16x16x32_bf16 v[120:123], v[162:165], v[186:189], v[120:123]
	v_mfma_f32_16x16x32_bf16 v[108:111], v[144:147], v[194:197], v[108:111]
	v_mfma_f32_16x16x32_bf16 v[104:107], v[162:165], v[194:197], v[104:107]
	v_mfma_f32_16x16x32_bf16 v[92:95], v[144:147], v[202:205], v[92:95]
	v_mfma_f32_16x16x32_bf16 v[88:91], v[162:165], v[202:205], v[88:91]
	v_mfma_f32_16x16x32_bf16 v[76:79], v[144:147], v[210:213], v[76:79]
	v_mfma_f32_16x16x32_bf16 v[72:75], v[162:165], v[210:213], v[72:75]
	v_mfma_f32_16x16x32_bf16 v[124:127], v[148:151], v[190:193], v[124:127]
	v_mfma_f32_16x16x32_bf16 v[120:123], v[166:169], v[190:193], v[120:123]
	v_mfma_f32_16x16x32_bf16 v[108:111], v[148:151], v[198:201], v[108:111]
	v_mfma_f32_16x16x32_bf16 v[104:107], v[166:169], v[198:201], v[104:107]
	v_mfma_f32_16x16x32_bf16 v[92:95], v[148:151], v[206:209], v[92:95]
	v_mfma_f32_16x16x32_bf16 v[88:91], v[166:169], v[206:209], v[88:91]
	v_mfma_f32_16x16x32_bf16 v[76:79], v[148:151], v[214:217], v[76:79]
	v_mfma_f32_16x16x32_bf16 v[72:75], v[166:169], v[214:217], v[72:75]
	s_setprio 0
	s_setprio 1
	v_mfma_f32_16x16x32_bf16 v[116:119], v[170:173], v[186:189], v[116:119]
	v_mfma_f32_16x16x32_bf16 v[112:115], v[178:181], v[186:189], v[112:115]
	v_mfma_f32_16x16x32_bf16 v[100:103], v[170:173], v[194:197], v[100:103]
	v_mfma_f32_16x16x32_bf16 v[96:99], v[178:181], v[194:197], v[96:99]
	v_mfma_f32_16x16x32_bf16 v[84:87], v[170:173], v[202:205], v[84:87]
	v_mfma_f32_16x16x32_bf16 v[80:83], v[178:181], v[202:205], v[80:83]
	v_mfma_f32_16x16x32_bf16 v[68:71], v[170:173], v[210:213], v[68:71]
	v_mfma_f32_16x16x32_bf16 v[64:67], v[178:181], v[210:213], v[64:67]
	v_mfma_f32_16x16x32_bf16 v[116:119], v[174:177], v[190:193], v[116:119]
	v_mfma_f32_16x16x32_bf16 v[112:115], v[182:185], v[190:193], v[112:115]
	v_mfma_f32_16x16x32_bf16 v[100:103], v[174:177], v[198:201], v[100:103]
	v_mfma_f32_16x16x32_bf16 v[96:99], v[182:185], v[198:201], v[96:99]
	v_mfma_f32_16x16x32_bf16 v[84:87], v[174:177], v[206:209], v[84:87]
	v_mfma_f32_16x16x32_bf16 v[80:83], v[182:185], v[206:209], v[80:83]
	v_mfma_f32_16x16x32_bf16 v[68:71], v[174:177], v[214:217], v[68:71]
	v_mfma_f32_16x16x32_bf16 v[64:67], v[182:185], v[214:217], v[64:67]
	s_setprio 0
	s_barrier
	s_add_i32 s50, s64, s21
	v_lshl_add_u64 v[152:153], v[152:153], 0, s[30:31]
	s_mov_b32 m0, s50
	s_nop 0
	global_load_lds_dwordx4 v[152:153], off
	s_add_i32 m0, s50, 0x2000
	s_add_u32 s48, s48, 0x80080
	v_lshl_add_u64 v[152:153], v[218:219], 0, s[30:31]
	s_addc_u32 s49, s49, 0
	s_add_i32 s50, s65, s21
	global_load_lds_dwordx4 v[152:153], off
	v_lshl_add_u64 v[152:153], v[222:223], 0, s[30:31]
	ds_read_b128 v[186:189], v161 offset:49152
	ds_read_b128 v[190:193], v161 offset:50176
	ds_read_b128 v[194:197], v161 offset:51200
	ds_read_b128 v[198:201], v161 offset:52224
	ds_read_b128 v[202:205], v161 offset:53248
	ds_read_b128 v[206:209], v161 offset:54272
	ds_read_b128 v[210:213], v161 offset:55296
	ds_read_b128 v[214:217], v161 offset:56320
	s_waitcnt vmcnt(4)
	s_waitcnt lgkmcnt(0)
	s_barrier
	s_setprio 1
	s_waitcnt lgkmcnt(0)
	v_mfma_f32_16x16x32_bf16 v[60:63], v[144:147], v[186:189], v[60:63]
	v_mfma_f32_16x16x32_bf16 v[56:59], v[162:165], v[186:189], v[56:59]
	v_lshl_add_u64 v[228:229], s[48:49], 0, v[130:131]
	s_mov_b32 m0, s50
	s_nop 0
	global_load_lds_dwordx4 v[228:229], off
	v_mfma_f32_16x16x32_bf16 v[44:47], v[144:147], v[194:197], v[44:47]
	v_mfma_f32_16x16x32_bf16 v[40:43], v[162:165], v[194:197], v[40:43]
	v_mfma_f32_16x16x32_bf16 v[28:31], v[144:147], v[202:205], v[28:31]
	v_mfma_f32_16x16x32_bf16 v[24:27], v[162:165], v[202:205], v[24:27]
	v_lshl_add_u64 v[228:229], s[48:49], 0, v[134:135]
	s_add_i32 m0, s50, 0x2000
	s_nop 0
	global_load_lds_dwordx4 v[228:229], off
	v_mfma_f32_16x16x32_bf16 v[12:15], v[144:147], v[210:213], v[12:15]
	v_mfma_f32_16x16x32_bf16 v[8:11], v[162:165], v[210:213], v[8:11]
	v_mfma_f32_16x16x32_bf16 v[60:63], v[148:151], v[190:193], v[60:63]
	v_mfma_f32_16x16x32_bf16 v[56:59], v[166:169], v[190:193], v[56:59]
	v_lshl_add_u64 v[228:229], v[220:221], 0, s[30:31]
	s_mov_b32 m0, s26
	s_nop 0
	global_load_lds_dwordx4 v[228:229], off
	v_mfma_f32_16x16x32_bf16 v[44:47], v[148:151], v[198:201], v[44:47]
	v_mfma_f32_16x16x32_bf16 v[40:43], v[166:169], v[198:201], v[40:43]
	v_mfma_f32_16x16x32_bf16 v[28:31], v[148:151], v[206:209], v[28:31]
	v_mfma_f32_16x16x32_bf16 v[24:27], v[166:169], v[206:209], v[24:27]
	s_mov_b32 m0, s27
	s_nop 0
	global_load_lds_dwordx4 v[152:153], off
	v_mfma_f32_16x16x32_bf16 v[12:15], v[148:151], v[214:217], v[12:15]
	v_mfma_f32_16x16x32_bf16 v[8:11], v[166:169], v[214:217], v[8:11]
	s_setprio 0
	s_setprio 1
	v_mfma_f32_16x16x32_bf16 v[52:55], v[170:173], v[186:189], v[52:55]
	v_mfma_f32_16x16x32_bf16 v[48:51], v[178:181], v[186:189], v[48:51]
	v_mfma_f32_16x16x32_bf16 v[36:39], v[170:173], v[194:197], v[36:39]
	v_mfma_f32_16x16x32_bf16 v[32:35], v[178:181], v[194:197], v[32:35]
	v_mfma_f32_16x16x32_bf16 v[20:23], v[170:173], v[202:205], v[20:23]
	v_mfma_f32_16x16x32_bf16 v[16:19], v[178:181], v[202:205], v[16:19]
	v_mfma_f32_16x16x32_bf16 v[4:7], v[170:173], v[210:213], v[4:7]
	v_mfma_f32_16x16x32_bf16 v[0:3], v[178:181], v[210:213], v[0:3]
	v_mfma_f32_16x16x32_bf16 v[52:55], v[174:177], v[190:193], v[52:55]
	v_mfma_f32_16x16x32_bf16 v[48:51], v[182:185], v[190:193], v[48:51]
	v_mfma_f32_16x16x32_bf16 v[36:39], v[174:177], v[198:201], v[36:39]
	v_mfma_f32_16x16x32_bf16 v[32:35], v[182:185], v[198:201], v[32:35]
	v_mfma_f32_16x16x32_bf16 v[20:23], v[174:177], v[206:209], v[20:23]
	v_mfma_f32_16x16x32_bf16 v[16:19], v[182:185], v[206:209], v[16:19]
	v_mfma_f32_16x16x32_bf16 v[4:7], v[174:177], v[214:217], v[4:7]
	v_mfma_f32_16x16x32_bf16 v[0:3], v[182:185], v[214:217], v[0:3]
	s_setprio 0
	s_barrier
	s_add_i32 s63, s63, 2
	s_add_u32 s46, s46, 0x100
	s_addc_u32 s47, s47, 0
	s_add_u32 s45, s45, 0x100
	s_addc_u32 s62, s62, 0
	s_cmp_gt_u32 s63, 29
	s_cbranch_scc0 .LBB0_1117
	s_and_b64 vcc, exec, s[16:17]
	s_cbranch_vccz .LBB0_1120
	s_barrier

.LBB0_1240:
	ds_read_b128 v[144:147], v153
	ds_read_b128 v[158:161], v153 offset:1024
	ds_read_b128 v[162:165], v153 offset:2048
	ds_read_b128 v[166:169], v153 offset:3072
	ds_read_b128 v[170:173], v154
	ds_read_b128 v[174:177], v154 offset:1024
	ds_read_b128 v[178:181], v154 offset:2048
	ds_read_b128 v[182:185], v154 offset:3072
	s_add_u32 s40, s38, 0x100
	s_addc_u32 s41, s39, 0
	s_cmp_eq_u32 s61, 28
	s_cselect_b32 s45, s29, s41
	s_cselect_b32 s44, s57, s40
	s_cselect_b32 s43, s19, s60
	s_cselect_b32 s42, s58, s59
	v_lshl_add_u64 v[148:149], s[38:39], 0, v[136:137]
	s_add_i32 m0, s37, 0xc000
	s_nop 0
	global_load_lds_dwordx4 v[148:149], off
	v_lshl_add_u64 v[148:149], s[38:39], 0, v[138:139]
	s_add_i32 m0, s37, 0xe000
	s_nop 0
	global_load_lds_dwordx4 v[148:149], off
	ds_read_b128 v[186:189], v155
	ds_read_b128 v[190:193], v155 offset:1024
	ds_read_b128 v[194:197], v155 offset:2048
	ds_read_b128 v[198:201], v155 offset:3072
	ds_read_b128 v[202:205], v155 offset:4096
	ds_read_b128 v[206:209], v155 offset:5120
	ds_read_b128 v[210:213], v155 offset:6144
	ds_read_b128 v[214:217], v155 offset:7168
	s_waitcnt vmcnt(8)
	s_waitcnt lgkmcnt(0)
	s_barrier
	s_setprio 1
	s_waitcnt lgkmcnt(0)
	v_mfma_f32_16x16x32_bf16 v[124:127], v[144:147], v[186:189], v[124:127]
	v_mfma_f32_16x16x32_bf16 v[120:123], v[162:165], v[186:189], v[120:123]
	v_mfma_f32_16x16x32_bf16 v[108:111], v[144:147], v[194:197], v[108:111]
	v_mfma_f32_16x16x32_bf16 v[104:107], v[162:165], v[194:197], v[104:107]
	v_mfma_f32_16x16x32_bf16 v[92:95], v[144:147], v[202:205], v[92:95]
	v_mfma_f32_16x16x32_bf16 v[88:91], v[162:165], v[202:205], v[88:91]
	v_mfma_f32_16x16x32_bf16 v[76:79], v[144:147], v[210:213], v[76:79]
	v_mfma_f32_16x16x32_bf16 v[72:75], v[162:165], v[210:213], v[72:75]
	v_mfma_f32_16x16x32_bf16 v[124:127], v[158:161], v[190:193], v[124:127]
	v_mfma_f32_16x16x32_bf16 v[120:123], v[166:169], v[190:193], v[120:123]
	v_mfma_f32_16x16x32_bf16 v[108:111], v[158:161], v[198:201], v[108:111]
	v_mfma_f32_16x16x32_bf16 v[104:107], v[166:169], v[198:201], v[104:107]
	v_mfma_f32_16x16x32_bf16 v[92:95], v[158:161], v[206:209], v[92:95]
	v_mfma_f32_16x16x32_bf16 v[88:91], v[166:169], v[206:209], v[88:91]
	v_mfma_f32_16x16x32_bf16 v[76:79], v[158:161], v[214:217], v[76:79]
	v_mfma_f32_16x16x32_bf16 v[72:75], v[166:169], v[214:217], v[72:75]
	s_setprio 0
	s_setprio 1
	v_mfma_f32_16x16x32_bf16 v[116:119], v[170:173], v[186:189], v[116:119]
	v_mfma_f32_16x16x32_bf16 v[112:115], v[178:181], v[186:189], v[112:115]
	v_mfma_f32_16x16x32_bf16 v[100:103], v[170:173], v[194:197], v[100:103]
	v_mfma_f32_16x16x32_bf16 v[96:99], v[178:181], v[194:197], v[96:99]
	v_mfma_f32_16x16x32_bf16 v[84:87], v[170:173], v[202:205], v[84:87]
	v_mfma_f32_16x16x32_bf16 v[80:83], v[178:181], v[202:205], v[80:83]
	v_mfma_f32_16x16x32_bf16 v[68:71], v[170:173], v[210:213], v[68:71]
	v_mfma_f32_16x16x32_bf16 v[64:67], v[178:181], v[210:213], v[64:67]
	v_mfma_f32_16x16x32_bf16 v[116:119], v[174:177], v[190:193], v[116:119]
	v_mfma_f32_16x16x32_bf16 v[112:115], v[182:185], v[190:193], v[112:115]
	v_mfma_f32_16x16x32_bf16 v[100:103], v[174:177], v[198:201], v[100:103]
	v_mfma_f32_16x16x32_bf16 v[96:99], v[182:185], v[198:201], v[96:99]
	v_mfma_f32_16x16x32_bf16 v[84:87], v[174:177], v[206:209], v[84:87]
	v_mfma_f32_16x16x32_bf16 v[80:83], v[182:185], v[206:209], v[80:83]
	v_mfma_f32_16x16x32_bf16 v[68:71], v[174:177], v[214:217], v[68:71]
	v_mfma_f32_16x16x32_bf16 v[64:67], v[182:185], v[214:217], v[64:67]
	s_setprio 0
	s_barrier
	s_add_i32 s38, s54, s21
	v_lshl_add_u64 v[148:149], s[42:43], 0, v[132:133]
	s_mov_b32 m0, s38
	v_lshl_add_u64 v[218:219], s[42:43], 0, v[128:129]
	global_load_lds_dwordx4 v[148:149], off
	s_add_i32 m0, s38, 0x2000
	s_add_u32 s38, s42, 0x80000
	s_addc_u32 s39, s43, 0
	s_add_i32 s62, s55, s21
	global_load_lds_dwordx4 v[218:219], off
	v_lshl_add_u64 v[220:221], s[44:45], 0, v[134:135]
	v_lshl_add_u64 v[222:223], s[44:45], 0, v[130:131]
	ds_read_b128 v[186:189], v155 offset:16384
	ds_read_b128 v[190:193], v155 offset:17408
	ds_read_b128 v[194:197], v155 offset:18432
	ds_read_b128 v[198:201], v155 offset:19456
	ds_read_b128 v[202:205], v155 offset:20480
	ds_read_b128 v[206:209], v155 offset:21504
	ds_read_b128 v[210:213], v155 offset:22528
	ds_read_b128 v[214:217], v155 offset:23552
	s_waitcnt vmcnt(4)
	s_waitcnt lgkmcnt(0)
	s_barrier
	s_setprio 1
	s_waitcnt lgkmcnt(0)
	v_mfma_f32_16x16x32_bf16 v[60:63], v[144:147], v[186:189], v[60:63]
	v_mfma_f32_16x16x32_bf16 v[56:59], v[162:165], v[186:189], v[56:59]
	v_lshl_add_u64 v[228:229], s[38:39], 0, v[132:133]
	s_mov_b32 m0, s62
	s_nop 0
	global_load_lds_dwordx4 v[228:229], off
	v_mfma_f32_16x16x32_bf16 v[44:47], v[144:147], v[194:197], v[44:47]
	v_mfma_f32_16x16x32_bf16 v[40:43], v[162:165], v[194:197], v[40:43]
	v_mfma_f32_16x16x32_bf16 v[28:31], v[144:147], v[202:205], v[28:31]
	v_mfma_f32_16x16x32_bf16 v[24:27], v[162:165], v[202:205], v[24:27]
	v_lshl_add_u64 v[228:229], s[38:39], 0, v[128:129]
	s_add_i32 m0, s62, 0x2000
	s_nop 0
	global_load_lds_dwordx4 v[228:229], off
	v_mfma_f32_16x16x32_bf16 v[12:15], v[144:147], v[210:213], v[12:15]
	v_mfma_f32_16x16x32_bf16 v[8:11], v[162:165], v[210:213], v[8:11]
	v_mfma_f32_16x16x32_bf16 v[60:63], v[158:161], v[190:193], v[60:63]
	v_mfma_f32_16x16x32_bf16 v[56:59], v[166:169], v[190:193], v[56:59]
	s_mov_b32 m0, s37
	s_nop 0
	global_load_lds_dwordx4 v[220:221], off
	v_mfma_f32_16x16x32_bf16 v[44:47], v[158:161], v[198:201], v[44:47]
	v_mfma_f32_16x16x32_bf16 v[40:43], v[166:169], v[198:201], v[40:43]
	v_mfma_f32_16x16x32_bf16 v[28:31], v[158:161], v[206:209], v[28:31]
	v_mfma_f32_16x16x32_bf16 v[24:27], v[166:169], v[206:209], v[24:27]
	s_mov_b32 m0, s47
	s_nop 0
	global_load_lds_dwordx4 v[222:223], off
	v_mfma_f32_16x16x32_bf16 v[12:15], v[158:161], v[214:217], v[12:15]
	v_mfma_f32_16x16x32_bf16 v[8:11], v[166:169], v[214:217], v[8:11]
	s_setprio 0
	s_setprio 1
	v_mfma_f32_16x16x32_bf16 v[52:55], v[170:173], v[186:189], v[52:55]
	v_mfma_f32_16x16x32_bf16 v[48:51], v[178:181], v[186:189], v[48:51]
	v_mfma_f32_16x16x32_bf16 v[36:39], v[170:173], v[194:197], v[36:39]
	v_mfma_f32_16x16x32_bf16 v[32:35], v[178:181], v[194:197], v[32:35]
	v_mfma_f32_16x16x32_bf16 v[20:23], v[170:173], v[202:205], v[20:23]
	v_mfma_f32_16x16x32_bf16 v[16:19], v[178:181], v[202:205], v[16:19]
	v_mfma_f32_16x16x32_bf16 v[4:7], v[170:173], v[210:213], v[4:7]
	v_mfma_f32_16x16x32_bf16 v[0:3], v[178:181], v[210:213], v[0:3]
	v_mfma_f32_16x16x32_bf16 v[52:55], v[174:177], v[190:193], v[52:55]
	v_mfma_f32_16x16x32_bf16 v[48:51], v[182:185], v[190:193], v[48:51]
	v_mfma_f32_16x16x32_bf16 v[36:39], v[174:177], v[198:201], v[36:39]
	v_mfma_f32_16x16x32_bf16 v[32:35], v[182:185], v[198:201], v[32:35]
	v_mfma_f32_16x16x32_bf16 v[20:23], v[174:177], v[206:209], v[20:23]
	v_mfma_f32_16x16x32_bf16 v[16:19], v[182:185], v[206:209], v[16:19]
	v_mfma_f32_16x16x32_bf16 v[4:7], v[174:177], v[214:217], v[4:7]
	v_mfma_f32_16x16x32_bf16 v[0:3], v[182:185], v[214:217], v[0:3]
	s_setprio 0
	s_barrier
	s_add_i32 s62, 0, 0x18000
	v_add_u32_e32 v157, s62, v150
	s_add_i32 s63, 0, 0x1c000
	ds_read_b128 v[144:147], v157
	ds_read_b128 v[158:161], v157 offset:1024
	ds_read_b128 v[162:165], v157 offset:2048
	ds_read_b128 v[166:169], v157 offset:3072
	v_add_u32_e32 v157, s63, v150
	ds_read_b128 v[170:173], v157
	ds_read_b128 v[174:177], v157 offset:1024
	ds_read_b128 v[178:181], v157 offset:2048
	ds_read_b128 v[182:185], v157 offset:3072
	s_add_u32 s38, s44, 0x80000
	s_addc_u32 s39, s45, 0
	s_mov_b32 m0, s48
	v_lshl_add_u64 v[186:187], s[38:39], 0, v[134:135]
	global_load_lds_dwordx4 v[186:187], off
	v_lshl_add_u64 v[186:187], s[38:39], 0, v[130:131]
	s_mov_b32 m0, s49
	s_nop 0
	global_load_lds_dwordx4 v[186:187], off
	ds_read_b128 v[186:189], v155 offset:32768
	ds_read_b128 v[190:193], v155 offset:33792
	ds_read_b128 v[194:197], v155 offset:34816
	ds_read_b128 v[198:201], v155 offset:35840
	ds_read_b128 v[202:205], v155 offset:36864
	ds_read_b128 v[206:209], v155 offset:37888
	ds_read_b128 v[210:213], v155 offset:38912
	ds_read_b128 v[214:217], v155 offset:39936
	s_waitcnt vmcnt(8)
	s_waitcnt lgkmcnt(0)
	s_barrier
	s_setprio 1
	s_waitcnt lgkmcnt(0)
	v_mfma_f32_16x16x32_bf16 v[124:127], v[144:147], v[186:189], v[124:127]
	v_mfma_f32_16x16x32_bf16 v[120:123], v[162:165], v[186:189], v[120:123]
	v_mfma_f32_16x16x32_bf16 v[108:111], v[144:147], v[194:197], v[108:111]
	v_mfma_f32_16x16x32_bf16 v[104:107], v[162:165], v[194:197], v[104:107]
	v_mfma_f32_16x16x32_bf16 v[92:95], v[144:147], v[202:205], v[92:95]
	v_mfma_f32_16x16x32_bf16 v[88:91], v[162:165], v[202:205], v[88:91]
	v_mfma_f32_16x16x32_bf16 v[76:79], v[144:147], v[210:213], v[76:79]
	v_mfma_f32_16x16x32_bf16 v[72:75], v[162:165], v[210:213], v[72:75]
	v_mfma_f32_16x16x32_bf16 v[124:127], v[158:161], v[190:193], v[124:127]
	v_mfma_f32_16x16x32_bf16 v[120:123], v[166:169], v[190:193], v[120:123]
	v_mfma_f32_16x16x32_bf16 v[108:111], v[158:161], v[198:201], v[108:111]
	v_mfma_f32_16x16x32_bf16 v[104:107], v[166:169], v[198:201], v[104:107]
	v_mfma_f32_16x16x32_bf16 v[92:95], v[158:161], v[206:209], v[92:95]
	v_mfma_f32_16x16x32_bf16 v[88:91], v[166:169], v[206:209], v[88:91]
	v_mfma_f32_16x16x32_bf16 v[76:79], v[158:161], v[214:217], v[76:79]
	v_mfma_f32_16x16x32_bf16 v[72:75], v[166:169], v[214:217], v[72:75]
	s_setprio 0
	s_setprio 1
	v_mfma_f32_16x16x32_bf16 v[116:119], v[170:173], v[186:189], v[116:119]
	v_mfma_f32_16x16x32_bf16 v[112:115], v[178:181], v[186:189], v[112:115]
	v_mfma_f32_16x16x32_bf16 v[100:103], v[170:173], v[194:197], v[100:103]
	v_mfma_f32_16x16x32_bf16 v[96:99], v[178:181], v[194:197], v[96:99]
	v_mfma_f32_16x16x32_bf16 v[84:87], v[170:173], v[202:205], v[84:87]
	v_mfma_f32_16x16x32_bf16 v[80:83], v[178:181], v[202:205], v[80:83]
	v_mfma_f32_16x16x32_bf16 v[68:71], v[170:173], v[210:213], v[68:71]
	v_mfma_f32_16x16x32_bf16 v[64:67], v[178:181], v[210:213], v[64:67]
	v_mfma_f32_16x16x32_bf16 v[116:119], v[174:177], v[190:193], v[116:119]
	v_mfma_f32_16x16x32_bf16 v[112:115], v[182:185], v[190:193], v[112:115]
	v_mfma_f32_16x16x32_bf16 v[100:103], v[174:177], v[198:201], v[100:103]
	v_mfma_f32_16x16x32_bf16 v[96:99], v[182:185], v[198:201], v[96:99]
	v_mfma_f32_16x16x32_bf16 v[84:87], v[174:177], v[206:209], v[84:87]
	v_mfma_f32_16x16x32_bf16 v[80:83], v[182:185], v[206:209], v[80:83]
	v_mfma_f32_16x16x32_bf16 v[68:71], v[174:177], v[214:217], v[68:71]
	v_mfma_f32_16x16x32_bf16 v[64:67], v[182:185], v[214:217], v[64:67]
	s_setprio 0
	s_barrier
	s_add_i32 s38, s62, s21
	v_lshl_add_u64 v[148:149], v[148:149], 0, s[16:17]
	s_mov_b32 m0, s38
	s_nop 0
	global_load_lds_dwordx4 v[148:149], off
	s_add_i32 m0, s38, 0x2000
	s_add_u32 s38, s42, 0x80080
	v_lshl_add_u64 v[148:149], v[218:219], 0, s[16:17]
	s_addc_u32 s39, s43, 0
	s_add_i32 s42, s63, s21
	global_load_lds_dwordx4 v[148:149], off
	v_lshl_add_u64 v[148:149], v[222:223], 0, s[16:17]
	ds_read_b128 v[186:189], v155 offset:49152
	ds_read_b128 v[190:193], v155 offset:50176
	ds_read_b128 v[194:197], v155 offset:51200
	ds_read_b128 v[198:201], v155 offset:52224
	ds_read_b128 v[202:205], v155 offset:53248
	ds_read_b128 v[206:209], v155 offset:54272
	ds_read_b128 v[210:213], v155 offset:55296
	ds_read_b128 v[214:217], v155 offset:56320
	s_waitcnt vmcnt(4)
	s_waitcnt lgkmcnt(0)
	s_barrier
	s_setprio 1
	s_waitcnt lgkmcnt(0)
	v_mfma_f32_16x16x32_bf16 v[60:63], v[144:147], v[186:189], v[60:63]
	v_mfma_f32_16x16x32_bf16 v[56:59], v[162:165], v[186:189], v[56:59]
	v_lshl_add_u64 v[228:229], s[38:39], 0, v[132:133]
	s_mov_b32 m0, s42
	s_nop 0
	global_load_lds_dwordx4 v[228:229], off
	v_mfma_f32_16x16x32_bf16 v[44:47], v[144:147], v[194:197], v[44:47]
	v_mfma_f32_16x16x32_bf16 v[40:43], v[162:165], v[194:197], v[40:43]
	v_mfma_f32_16x16x32_bf16 v[28:31], v[144:147], v[202:205], v[28:31]
	v_mfma_f32_16x16x32_bf16 v[24:27], v[162:165], v[202:205], v[24:27]
	v_lshl_add_u64 v[228:229], s[38:39], 0, v[128:129]
	s_add_i32 m0, s42, 0x2000
	s_nop 0
	global_load_lds_dwordx4 v[228:229], off
	v_mfma_f32_16x16x32_bf16 v[12:15], v[144:147], v[210:213], v[12:15]
	v_mfma_f32_16x16x32_bf16 v[8:11], v[162:165], v[210:213], v[8:11]
	v_mfma_f32_16x16x32_bf16 v[60:63], v[158:161], v[190:193], v[60:63]
	v_mfma_f32_16x16x32_bf16 v[56:59], v[166:169], v[190:193], v[56:59]
	v_lshl_add_u64 v[228:229], v[220:221], 0, s[16:17]
	s_mov_b32 m0, s51
	s_nop 0
	global_load_lds_dwordx4 v[228:229], off
	v_mfma_f32_16x16x32_bf16 v[44:47], v[158:161], v[198:201], v[44:47]
	v_mfma_f32_16x16x32_bf16 v[40:43], v[166:169], v[198:201], v[40:43]
	v_mfma_f32_16x16x32_bf16 v[28:31], v[158:161], v[206:209], v[28:31]
	v_mfma_f32_16x16x32_bf16 v[24:27], v[166:169], v[206:209], v[24:27]
	s_mov_b32 m0, s52
	s_nop 0
	global_load_lds_dwordx4 v[148:149], off
	v_mfma_f32_16x16x32_bf16 v[12:15], v[158:161], v[214:217], v[12:15]
	v_mfma_f32_16x16x32_bf16 v[8:11], v[166:169], v[214:217], v[8:11]
	s_setprio 0
	s_setprio 1
	v_mfma_f32_16x16x32_bf16 v[52:55], v[170:173], v[186:189], v[52:55]
	v_mfma_f32_16x16x32_bf16 v[48:51], v[178:181], v[186:189], v[48:51]
	v_mfma_f32_16x16x32_bf16 v[36:39], v[170:173], v[194:197], v[36:39]
	v_mfma_f32_16x16x32_bf16 v[32:35], v[178:181], v[194:197], v[32:35]
	v_mfma_f32_16x16x32_bf16 v[20:23], v[170:173], v[202:205], v[20:23]
	v_mfma_f32_16x16x32_bf16 v[16:19], v[178:181], v[202:205], v[16:19]
	v_mfma_f32_16x16x32_bf16 v[4:7], v[170:173], v[210:213], v[4:7]
	v_mfma_f32_16x16x32_bf16 v[0:3], v[178:181], v[210:213], v[0:3]
	v_mfma_f32_16x16x32_bf16 v[52:55], v[174:177], v[190:193], v[52:55]
	v_mfma_f32_16x16x32_bf16 v[48:51], v[182:185], v[190:193], v[48:51]
	v_mfma_f32_16x16x32_bf16 v[36:39], v[174:177], v[198:201], v[36:39]
	v_mfma_f32_16x16x32_bf16 v[32:35], v[182:185], v[198:201], v[32:35]
	v_mfma_f32_16x16x32_bf16 v[20:23], v[174:177], v[206:209], v[20:23]
	v_mfma_f32_16x16x32_bf16 v[16:19], v[182:185], v[206:209], v[16:19]
	v_mfma_f32_16x16x32_bf16 v[4:7], v[174:177], v[214:217], v[4:7]
	v_mfma_f32_16x16x32_bf16 v[0:3], v[182:185], v[214:217], v[0:3]
	s_setprio 0
	s_barrier
	s_add_i32 s61, s61, 2
	s_add_u32 s59, s59, 0x100
	s_addc_u32 s60, s60, 0
	s_cmp_gt_u32 s61, 29
	s_mov_b64 s[38:39], s[40:41]
	s_cbranch_scc0 .LBB0_1240
	s_and_b64 vcc, exec, s[6:7]
	s_cbranch_vccz .LBB0_1243
	s_barrier

.LBB0_1327:
	ds_read_b128 v[144:147], v151
	ds_read_b128 v[154:157], v151 offset:1024
	ds_read_b128 v[158:161], v151 offset:2048
	ds_read_b128 v[162:165], v151 offset:3072
	ds_read_b128 v[166:169], v152
	ds_read_b128 v[170:173], v152 offset:1024
	ds_read_b128 v[174:177], v152 offset:2048
	ds_read_b128 v[178:181], v152 offset:3072
	s_add_u32 s34, s30, 0x100
	s_addc_u32 s35, s31, 0
	s_cmpk_eq_i32 s55, 0x54
	s_cselect_b32 s39, s5, s35
	s_cselect_b32 s38, s4, s34
	s_cselect_b32 s37, s29, s54
	s_cselect_b32 s36, s28, s53
	v_lshl_add_u64 v[182:183], s[30:31], 0, v[136:137]
	s_add_i32 m0, s40, 0xc000
	s_nop 0
	global_load_lds_dwordx4 v[182:183], off
	v_lshl_add_u64 v[182:183], s[30:31], 0, v[138:139]
	s_add_i32 m0, s40, 0xe000
	s_nop 0
	global_load_lds_dwordx4 v[182:183], off
	ds_read_b128 v[182:185], v153
	ds_read_b128 v[186:189], v153 offset:1024
	ds_read_b128 v[190:193], v153 offset:2048
	ds_read_b128 v[194:197], v153 offset:3072
	ds_read_b128 v[198:201], v153 offset:4096
	ds_read_b128 v[202:205], v153 offset:5120
	ds_read_b128 v[206:209], v153 offset:6144
	ds_read_b128 v[210:213], v153 offset:7168
	s_waitcnt vmcnt(8)
	s_waitcnt lgkmcnt(0)
	s_barrier
	s_setprio 1
	s_waitcnt lgkmcnt(0)
	v_mfma_f32_16x16x32_bf16 v[124:127], v[144:147], v[182:185], v[124:127]
	v_mfma_f32_16x16x32_bf16 v[120:123], v[158:161], v[182:185], v[120:123]
	v_mfma_f32_16x16x32_bf16 v[108:111], v[144:147], v[190:193], v[108:111]
	v_mfma_f32_16x16x32_bf16 v[104:107], v[158:161], v[190:193], v[104:107]
	v_mfma_f32_16x16x32_bf16 v[92:95], v[144:147], v[198:201], v[92:95]
	v_mfma_f32_16x16x32_bf16 v[88:91], v[158:161], v[198:201], v[88:91]
	v_mfma_f32_16x16x32_bf16 v[76:79], v[144:147], v[206:209], v[76:79]
	v_mfma_f32_16x16x32_bf16 v[72:75], v[158:161], v[206:209], v[72:75]
	v_mfma_f32_16x16x32_bf16 v[124:127], v[154:157], v[186:189], v[124:127]
	v_mfma_f32_16x16x32_bf16 v[120:123], v[162:165], v[186:189], v[120:123]
	v_mfma_f32_16x16x32_bf16 v[108:111], v[154:157], v[194:197], v[108:111]
	v_mfma_f32_16x16x32_bf16 v[104:107], v[162:165], v[194:197], v[104:107]
	v_mfma_f32_16x16x32_bf16 v[92:95], v[154:157], v[202:205], v[92:95]
	v_mfma_f32_16x16x32_bf16 v[88:91], v[162:165], v[202:205], v[88:91]
	v_mfma_f32_16x16x32_bf16 v[76:79], v[154:157], v[210:213], v[76:79]
	v_mfma_f32_16x16x32_bf16 v[72:75], v[162:165], v[210:213], v[72:75]
	s_setprio 0
	s_setprio 1
	v_mfma_f32_16x16x32_bf16 v[116:119], v[166:169], v[182:185], v[116:119]
	v_mfma_f32_16x16x32_bf16 v[112:115], v[174:177], v[182:185], v[112:115]
	v_mfma_f32_16x16x32_bf16 v[100:103], v[166:169], v[190:193], v[100:103]
	v_mfma_f32_16x16x32_bf16 v[96:99], v[174:177], v[190:193], v[96:99]
	v_mfma_f32_16x16x32_bf16 v[84:87], v[166:169], v[198:201], v[84:87]
	v_mfma_f32_16x16x32_bf16 v[80:83], v[174:177], v[198:201], v[80:83]
	v_mfma_f32_16x16x32_bf16 v[68:71], v[166:169], v[206:209], v[68:71]
	v_mfma_f32_16x16x32_bf16 v[64:67], v[174:177], v[206:209], v[64:67]
	v_mfma_f32_16x16x32_bf16 v[116:119], v[170:173], v[186:189], v[116:119]
	v_mfma_f32_16x16x32_bf16 v[112:115], v[178:181], v[186:189], v[112:115]
	v_mfma_f32_16x16x32_bf16 v[100:103], v[170:173], v[194:197], v[100:103]
	v_mfma_f32_16x16x32_bf16 v[96:99], v[178:181], v[194:197], v[96:99]
	v_mfma_f32_16x16x32_bf16 v[84:87], v[170:173], v[202:205], v[84:87]
	v_mfma_f32_16x16x32_bf16 v[80:83], v[178:181], v[202:205], v[80:83]
	v_mfma_f32_16x16x32_bf16 v[68:71], v[170:173], v[210:213], v[68:71]
	v_mfma_f32_16x16x32_bf16 v[64:67], v[178:181], v[210:213], v[64:67]
	s_setprio 0
	s_barrier
	s_add_i32 s30, s48, s23
	v_lshl_add_u64 v[214:215], s[36:37], 0, v[130:131]
	s_mov_b32 m0, s30
	v_lshl_add_u64 v[216:217], s[36:37], 0, v[134:135]
	global_load_lds_dwordx4 v[214:215], off
	s_add_i32 m0, s30, 0x2000
	s_add_u32 s30, s36, 0x160000
	s_addc_u32 s31, s37, 0
	s_add_i32 s56, s49, s23
	global_load_lds_dwordx4 v[216:217], off
	v_lshl_add_u64 v[218:219], s[38:39], 0, v[128:129]
	v_lshl_add_u64 v[220:221], s[38:39], 0, v[132:133]
	ds_read_b128 v[182:185], v153 offset:16384
	ds_read_b128 v[186:189], v153 offset:17408
	ds_read_b128 v[190:193], v153 offset:18432
	ds_read_b128 v[194:197], v153 offset:19456
	ds_read_b128 v[198:201], v153 offset:20480
	ds_read_b128 v[202:205], v153 offset:21504
	ds_read_b128 v[206:209], v153 offset:22528
	ds_read_b128 v[210:213], v153 offset:23552
	s_waitcnt vmcnt(4)
	s_waitcnt lgkmcnt(0)
	s_barrier
	s_setprio 1
	s_waitcnt lgkmcnt(0)
	v_mfma_f32_16x16x32_bf16 v[60:63], v[144:147], v[182:185], v[60:63]
	v_mfma_f32_16x16x32_bf16 v[56:59], v[158:161], v[182:185], v[56:59]
	v_lshl_add_u64 v[228:229], s[30:31], 0, v[130:131]
	s_mov_b32 m0, s56
	s_nop 0
	global_load_lds_dwordx4 v[228:229], off
	v_mfma_f32_16x16x32_bf16 v[44:47], v[144:147], v[190:193], v[44:47]
	v_mfma_f32_16x16x32_bf16 v[40:43], v[158:161], v[190:193], v[40:43]
	v_mfma_f32_16x16x32_bf16 v[28:31], v[144:147], v[198:201], v[28:31]
	v_mfma_f32_16x16x32_bf16 v[24:27], v[158:161], v[198:201], v[24:27]
	v_lshl_add_u64 v[228:229], s[30:31], 0, v[134:135]
	s_add_i32 m0, s56, 0x2000
	s_nop 0
	global_load_lds_dwordx4 v[228:229], off
	v_mfma_f32_16x16x32_bf16 v[12:15], v[144:147], v[206:209], v[12:15]
	v_mfma_f32_16x16x32_bf16 v[8:11], v[158:161], v[206:209], v[8:11]
	v_mfma_f32_16x16x32_bf16 v[60:63], v[154:157], v[186:189], v[60:63]
	v_mfma_f32_16x16x32_bf16 v[56:59], v[162:165], v[186:189], v[56:59]
	s_mov_b32 m0, s40
	s_nop 0
	global_load_lds_dwordx4 v[218:219], off
	v_mfma_f32_16x16x32_bf16 v[44:47], v[154:157], v[194:197], v[44:47]
	v_mfma_f32_16x16x32_bf16 v[40:43], v[162:165], v[194:197], v[40:43]
	v_mfma_f32_16x16x32_bf16 v[28:31], v[154:157], v[202:205], v[28:31]
	v_mfma_f32_16x16x32_bf16 v[24:27], v[162:165], v[202:205], v[24:27]
	s_mov_b32 m0, s41
	s_nop 0
	global_load_lds_dwordx4 v[220:221], off
	v_mfma_f32_16x16x32_bf16 v[12:15], v[154:157], v[210:213], v[12:15]
	v_mfma_f32_16x16x32_bf16 v[8:11], v[162:165], v[210:213], v[8:11]
	s_setprio 0
	s_setprio 1
	v_mfma_f32_16x16x32_bf16 v[52:55], v[166:169], v[182:185], v[52:55]
	v_mfma_f32_16x16x32_bf16 v[48:51], v[174:177], v[182:185], v[48:51]
	v_mfma_f32_16x16x32_bf16 v[36:39], v[166:169], v[190:193], v[36:39]
	v_mfma_f32_16x16x32_bf16 v[32:35], v[174:177], v[190:193], v[32:35]
	v_mfma_f32_16x16x32_bf16 v[20:23], v[166:169], v[198:201], v[20:23]
	v_mfma_f32_16x16x32_bf16 v[16:19], v[174:177], v[198:201], v[16:19]
	v_mfma_f32_16x16x32_bf16 v[4:7], v[166:169], v[206:209], v[4:7]
	v_mfma_f32_16x16x32_bf16 v[0:3], v[174:177], v[206:209], v[0:3]
	v_mfma_f32_16x16x32_bf16 v[52:55], v[170:173], v[186:189], v[52:55]
	v_mfma_f32_16x16x32_bf16 v[48:51], v[178:181], v[186:189], v[48:51]
	v_mfma_f32_16x16x32_bf16 v[36:39], v[170:173], v[194:197], v[36:39]
	v_mfma_f32_16x16x32_bf16 v[32:35], v[178:181], v[194:197], v[32:35]
	v_mfma_f32_16x16x32_bf16 v[20:23], v[170:173], v[202:205], v[20:23]
	v_mfma_f32_16x16x32_bf16 v[16:19], v[178:181], v[202:205], v[16:19]
	v_mfma_f32_16x16x32_bf16 v[4:7], v[170:173], v[210:213], v[4:7]
	v_mfma_f32_16x16x32_bf16 v[0:3], v[178:181], v[210:213], v[0:3]
	s_setprio 0
	s_barrier
	s_add_i32 s56, 0, 0x18000
	s_add_i32 s57, 0, 0x1c000
	v_add_u32_e32 v162, s56, v148
	v_add_u32_e32 v178, s57, v148
	ds_read_b128 v[144:147], v162
	ds_read_b128 v[154:157], v162 offset:1024
	ds_read_b128 v[158:161], v162 offset:2048
	ds_read_b128 v[162:165], v162 offset:3072
	ds_read_b128 v[166:169], v178
	ds_read_b128 v[170:173], v178 offset:1024
	ds_read_b128 v[174:177], v178 offset:2048
	ds_read_b128 v[178:181], v178 offset:3072
	s_add_u32 s30, s38, 0x160000
	s_addc_u32 s31, s39, 0
	s_mov_b32 m0, s42
	v_lshl_add_u64 v[182:183], s[30:31], 0, v[128:129]
	global_load_lds_dwordx4 v[182:183], off
	v_lshl_add_u64 v[182:183], s[30:31], 0, v[132:133]
	s_mov_b32 m0, s43
	s_nop 0
	global_load_lds_dwordx4 v[182:183], off
	ds_read_b128 v[182:185], v153 offset:32768
	ds_read_b128 v[186:189], v153 offset:33792
	ds_read_b128 v[190:193], v153 offset:34816
	ds_read_b128 v[194:197], v153 offset:35840
	ds_read_b128 v[198:201], v153 offset:36864
	ds_read_b128 v[202:205], v153 offset:37888
	ds_read_b128 v[206:209], v153 offset:38912
	ds_read_b128 v[210:213], v153 offset:39936
	s_waitcnt vmcnt(8)
	s_waitcnt lgkmcnt(0)
	s_barrier
	s_setprio 1
	s_waitcnt lgkmcnt(0)
	v_mfma_f32_16x16x32_bf16 v[124:127], v[144:147], v[182:185], v[124:127]
	v_mfma_f32_16x16x32_bf16 v[120:123], v[158:161], v[182:185], v[120:123]
	v_mfma_f32_16x16x32_bf16 v[108:111], v[144:147], v[190:193], v[108:111]
	v_mfma_f32_16x16x32_bf16 v[104:107], v[158:161], v[190:193], v[104:107]
	v_mfma_f32_16x16x32_bf16 v[92:95], v[144:147], v[198:201], v[92:95]
	v_mfma_f32_16x16x32_bf16 v[88:91], v[158:161], v[198:201], v[88:91]
	v_mfma_f32_16x16x32_bf16 v[76:79], v[144:147], v[206:209], v[76:79]
	v_mfma_f32_16x16x32_bf16 v[72:75], v[158:161], v[206:209], v[72:75]
	v_mfma_f32_16x16x32_bf16 v[124:127], v[154:157], v[186:189], v[124:127]
	v_mfma_f32_16x16x32_bf16 v[120:123], v[162:165], v[186:189], v[120:123]
	v_mfma_f32_16x16x32_bf16 v[108:111], v[154:157], v[194:197], v[108:111]
	v_mfma_f32_16x16x32_bf16 v[104:107], v[162:165], v[194:197], v[104:107]
	v_mfma_f32_16x16x32_bf16 v[92:95], v[154:157], v[202:205], v[92:95]
	v_mfma_f32_16x16x32_bf16 v[88:91], v[162:165], v[202:205], v[88:91]
	v_mfma_f32_16x16x32_bf16 v[76:79], v[154:157], v[210:213], v[76:79]
	v_mfma_f32_16x16x32_bf16 v[72:75], v[162:165], v[210:213], v[72:75]
	s_setprio 0
	s_setprio 1
	v_mfma_f32_16x16x32_bf16 v[116:119], v[166:169], v[182:185], v[116:119]
	v_mfma_f32_16x16x32_bf16 v[112:115], v[174:177], v[182:185], v[112:115]
	v_mfma_f32_16x16x32_bf16 v[100:103], v[166:169], v[190:193], v[100:103]
	v_mfma_f32_16x16x32_bf16 v[96:99], v[174:177], v[190:193], v[96:99]
	v_mfma_f32_16x16x32_bf16 v[84:87], v[166:169], v[198:201], v[84:87]
	v_mfma_f32_16x16x32_bf16 v[80:83], v[174:177], v[198:201], v[80:83]
	v_mfma_f32_16x16x32_bf16 v[68:71], v[166:169], v[206:209], v[68:71]
	v_mfma_f32_16x16x32_bf16 v[64:67], v[174:177], v[206:209], v[64:67]
	v_mfma_f32_16x16x32_bf16 v[116:119], v[170:173], v[186:189], v[116:119]
	v_mfma_f32_16x16x32_bf16 v[112:115], v[178:181], v[186:189], v[112:115]
	v_mfma_f32_16x16x32_bf16 v[100:103], v[170:173], v[194:197], v[100:103]
	v_mfma_f32_16x16x32_bf16 v[96:99], v[178:181], v[194:197], v[96:99]
	v_mfma_f32_16x16x32_bf16 v[84:87], v[170:173], v[202:205], v[84:87]
	v_mfma_f32_16x16x32_bf16 v[80:83], v[178:181], v[202:205], v[80:83]
	v_mfma_f32_16x16x32_bf16 v[68:71], v[170:173], v[210:213], v[68:71]
	v_mfma_f32_16x16x32_bf16 v[64:67], v[178:181], v[210:213], v[64:67]
	s_setprio 0
	s_barrier
	s_add_i32 s30, s56, s23
	v_lshl_add_u64 v[182:183], v[214:215], 0, s[16:17]
	s_mov_b32 m0, s30
	s_nop 0
	global_load_lds_dwordx4 v[182:183], off
	s_add_i32 m0, s30, 0x2000
	s_add_u32 s30, s36, 0x160080
	v_lshl_add_u64 v[182:183], v[216:217], 0, s[16:17]
	s_addc_u32 s31, s37, 0
	s_add_i32 s36, s57, s23
	global_load_lds_dwordx4 v[182:183], off
	ds_read_b128 v[182:185], v153 offset:49152
	ds_read_b128 v[186:189], v153 offset:50176
	ds_read_b128 v[190:193], v153 offset:51200
	ds_read_b128 v[194:197], v153 offset:52224
	ds_read_b128 v[198:201], v153 offset:53248
	ds_read_b128 v[202:205], v153 offset:54272
	ds_read_b128 v[206:209], v153 offset:55296
	ds_read_b128 v[210:213], v153 offset:56320
	s_waitcnt vmcnt(4)
	s_waitcnt lgkmcnt(0)
	s_barrier
	s_setprio 1
	s_waitcnt lgkmcnt(0)
	v_mfma_f32_16x16x32_bf16 v[60:63], v[144:147], v[182:185], v[60:63]
	v_mfma_f32_16x16x32_bf16 v[56:59], v[158:161], v[182:185], v[56:59]
	v_lshl_add_u64 v[228:229], s[30:31], 0, v[130:131]
	s_mov_b32 m0, s36
	s_nop 0
	global_load_lds_dwordx4 v[228:229], off
	v_mfma_f32_16x16x32_bf16 v[44:47], v[144:147], v[190:193], v[44:47]
	v_mfma_f32_16x16x32_bf16 v[40:43], v[158:161], v[190:193], v[40:43]
	v_mfma_f32_16x16x32_bf16 v[28:31], v[144:147], v[198:201], v[28:31]
	v_mfma_f32_16x16x32_bf16 v[24:27], v[158:161], v[198:201], v[24:27]
	v_lshl_add_u64 v[228:229], s[30:31], 0, v[134:135]
	s_add_i32 m0, s36, 0x2000
	s_nop 0
	global_load_lds_dwordx4 v[228:229], off
	v_mfma_f32_16x16x32_bf16 v[12:15], v[144:147], v[206:209], v[12:15]
	v_mfma_f32_16x16x32_bf16 v[8:11], v[158:161], v[206:209], v[8:11]
	v_mfma_f32_16x16x32_bf16 v[60:63], v[154:157], v[186:189], v[60:63]
	v_mfma_f32_16x16x32_bf16 v[56:59], v[162:165], v[186:189], v[56:59]
	v_lshl_add_u64 v[228:229], v[218:219], 0, s[16:17]
	s_mov_b32 m0, s45
	s_nop 0
	global_load_lds_dwordx4 v[228:229], off
	v_mfma_f32_16x16x32_bf16 v[44:47], v[154:157], v[194:197], v[44:47]
	v_mfma_f32_16x16x32_bf16 v[40:43], v[162:165], v[194:197], v[40:43]
	v_mfma_f32_16x16x32_bf16 v[28:31], v[154:157], v[202:205], v[28:31]
	v_mfma_f32_16x16x32_bf16 v[24:27], v[162:165], v[202:205], v[24:27]
	v_lshl_add_u64 v[228:229], v[220:221], 0, s[16:17]
	s_mov_b32 m0, s46
	s_nop 0
	global_load_lds_dwordx4 v[228:229], off
	v_mfma_f32_16x16x32_bf16 v[12:15], v[154:157], v[210:213], v[12:15]
	v_mfma_f32_16x16x32_bf16 v[8:11], v[162:165], v[210:213], v[8:11]
	s_setprio 0
	s_setprio 1
	v_mfma_f32_16x16x32_bf16 v[52:55], v[166:169], v[182:185], v[52:55]
	v_mfma_f32_16x16x32_bf16 v[48:51], v[174:177], v[182:185], v[48:51]
	v_mfma_f32_16x16x32_bf16 v[36:39], v[166:169], v[190:193], v[36:39]
	v_mfma_f32_16x16x32_bf16 v[32:35], v[174:177], v[190:193], v[32:35]
	v_mfma_f32_16x16x32_bf16 v[20:23], v[166:169], v[198:201], v[20:23]
	v_mfma_f32_16x16x32_bf16 v[16:19], v[174:177], v[198:201], v[16:19]
	v_mfma_f32_16x16x32_bf16 v[4:7], v[166:169], v[206:209], v[4:7]
	v_mfma_f32_16x16x32_bf16 v[0:3], v[174:177], v[206:209], v[0:3]
	v_mfma_f32_16x16x32_bf16 v[52:55], v[170:173], v[186:189], v[52:55]
	v_mfma_f32_16x16x32_bf16 v[48:51], v[178:181], v[186:189], v[48:51]
	v_mfma_f32_16x16x32_bf16 v[36:39], v[170:173], v[194:197], v[36:39]
	v_mfma_f32_16x16x32_bf16 v[32:35], v[178:181], v[194:197], v[32:35]
	v_mfma_f32_16x16x32_bf16 v[20:23], v[170:173], v[202:205], v[20:23]
	v_mfma_f32_16x16x32_bf16 v[16:19], v[178:181], v[202:205], v[16:19]
	v_mfma_f32_16x16x32_bf16 v[4:7], v[170:173], v[210:213], v[4:7]
	v_mfma_f32_16x16x32_bf16 v[0:3], v[178:181], v[210:213], v[0:3]
	s_setprio 0
	s_barrier
	s_add_i32 s55, s55, 2
	s_add_u32 s53, s53, 0x100
	s_addc_u32 s54, s54, 0
	s_cmpk_gt_u32 s55, 0x55
	s_mov_b64 s[30:31], s[34:35]
	s_cbranch_scc0 .LBB0_1327
	s_and_b64 vcc, exec, s[8:9]
	s_cbranch_vccz .LBB0_1330
	s_barrier
